# gla_scan register ring: loads issued 13 steps ahead instead of 8
# baseline (speedup 1.0000x reference)
.LBB0_724:
	s_and_b64 s[10:11], vcc, exec
	s_mov_b32 s12, 0x8000
	s_mov_b32 s18, 0xffff8000
	s_movk_i32 s14, 0x200
	s_mov_b32 s19, 0xfffffe00
	s_cmp_lg_u64 s[10:11], 0
	s_cselect_b32 s12, s12, s18
	s_cselect_b32 s13, 0, -1
	s_cselect_b32 s14, s14, s19
	s_cselect_b32 s15, 0, -1
	s_cselect_b32 s16, 0, 63
	s_mov_b32 s17, 0
	s_lshl_b32 s18, s16, 15
	s_mov_b32 s19, 0
	v_lshl_add_u64 v[34:35], v[8:9], 0, s[18:19]
	v_lshl_add_u64 v[38:39], v[10:11], 0, s[16:17]
	v_lshlrev_b64 v[38:39], 9, v[38:39]
	v_lshl_add_u64 v[38:39], v[38:39], 0, v[6:7]
	v_mov_b32_e32 v36, v34
	v_mov_b32_e32 v37, v35
	global_load_dwordx4 v[40:43], v[34:35], off
	global_load_dwordx4 v[104:107], v[38:39], off
	global_load_dwordx4 v[170:173], v[38:39], off offset:16
	v_lshl_add_u64 v[34:35], v[34:35], 0, s[12:13]
	v_lshl_add_u64 v[38:39], v[38:39], 0, s[14:15]
	global_load_dwordx4 v[44:47], v[34:35], off
	global_load_dwordx4 v[108:111], v[38:39], off
	global_load_dwordx4 v[174:177], v[38:39], off offset:16
	v_lshl_add_u64 v[34:35], v[34:35], 0, s[12:13]
	v_lshl_add_u64 v[38:39], v[38:39], 0, s[14:15]
	global_load_dwordx4 v[48:51], v[34:35], off
	global_load_dwordx4 v[112:115], v[38:39], off
	global_load_dwordx4 v[178:181], v[38:39], off offset:16
	v_lshl_add_u64 v[34:35], v[34:35], 0, s[12:13]
	v_lshl_add_u64 v[38:39], v[38:39], 0, s[14:15]
	global_load_dwordx4 v[52:55], v[34:35], off
	global_load_dwordx4 v[116:119], v[38:39], off
	global_load_dwordx4 v[186:189], v[38:39], off offset:16
	v_lshl_add_u64 v[34:35], v[34:35], 0, s[12:13]
	v_lshl_add_u64 v[38:39], v[38:39], 0, s[14:15]
	global_load_dwordx4 v[56:59], v[34:35], off
	global_load_dwordx4 v[120:123], v[38:39], off
	global_load_dwordx4 v[190:193], v[38:39], off offset:16
	v_lshl_add_u64 v[34:35], v[34:35], 0, s[12:13]
	v_lshl_add_u64 v[38:39], v[38:39], 0, s[14:15]
	global_load_dwordx4 v[60:63], v[34:35], off
	global_load_dwordx4 v[124:127], v[38:39], off
	global_load_dwordx4 v[194:197], v[38:39], off offset:16
	v_lshl_add_u64 v[34:35], v[34:35], 0, s[12:13]
	v_lshl_add_u64 v[38:39], v[38:39], 0, s[14:15]
	global_load_dwordx4 v[64:67], v[34:35], off
	global_load_dwordx4 v[128:131], v[38:39], off
	global_load_dwordx4 v[198:201], v[38:39], off offset:16
	v_lshl_add_u64 v[34:35], v[34:35], 0, s[12:13]
	v_lshl_add_u64 v[38:39], v[38:39], 0, s[14:15]
	global_load_dwordx4 v[68:71], v[34:35], off
	global_load_dwordx4 v[132:135], v[38:39], off
	global_load_dwordx4 v[202:205], v[38:39], off offset:16
	v_lshl_add_u64 v[34:35], v[34:35], 0, s[12:13]
	v_lshl_add_u64 v[38:39], v[38:39], 0, s[14:15]
	global_load_dwordx4 v[72:75], v[34:35], off
	global_load_dwordx4 v[136:139], v[38:39], off
	global_load_dwordx4 v[206:209], v[38:39], off offset:16
	v_lshl_add_u64 v[34:35], v[34:35], 0, s[12:13]
	v_lshl_add_u64 v[38:39], v[38:39], 0, s[14:15]
	global_load_dwordx4 v[76:79], v[34:35], off
	global_load_dwordx4 v[140:143], v[38:39], off
	global_load_dwordx4 v[210:213], v[38:39], off offset:16
	v_lshl_add_u64 v[34:35], v[34:35], 0, s[12:13]
	v_lshl_add_u64 v[38:39], v[38:39], 0, s[14:15]
	global_load_dwordx4 v[80:83], v[34:35], off
	global_load_dwordx4 v[146:149], v[38:39], off
	global_load_dwordx4 v[214:217], v[38:39], off offset:16
	v_lshl_add_u64 v[34:35], v[34:35], 0, s[12:13]
	v_lshl_add_u64 v[38:39], v[38:39], 0, s[14:15]
	global_load_dwordx4 v[84:87], v[34:35], off
	global_load_dwordx4 v[150:153], v[38:39], off
	global_load_dwordx4 v[218:221], v[38:39], off offset:16
	v_lshl_add_u64 v[34:35], v[34:35], 0, s[12:13]
	v_lshl_add_u64 v[38:39], v[38:39], 0, s[14:15]
	global_load_dwordx4 v[88:91], v[34:35], off
	global_load_dwordx4 v[154:157], v[38:39], off
	global_load_dwordx4 v[222:225], v[38:39], off offset:16
	v_lshl_add_u64 v[34:35], v[34:35], 0, s[12:13]
	v_lshl_add_u64 v[38:39], v[38:39], 0, s[14:15]
	global_load_dwordx4 v[92:95], v[34:35], off
	global_load_dwordx4 v[158:161], v[38:39], off
	global_load_dwordx4 v[226:229], v[38:39], off offset:16
	v_lshl_add_u64 v[34:35], v[34:35], 0, s[12:13]
	v_lshl_add_u64 v[38:39], v[38:39], 0, s[14:15]
	s_waitcnt vmcnt(39)
	v_cvt_pk_bf16_f32 v0, v12, v13
	v_cvt_pk_bf16_f32 v1, v14, v15
	v_cvt_pk_bf16_f32 v2, v16, v17
	v_cvt_pk_bf16_f32 v3, v18, v19
	v_lshlrev_b32_e32 v26, 16, v40
	v_and_b32_e32 v27, 0xffff0000, v40
	v_lshlrev_b32_e32 v28, 16, v41
	v_and_b32_e32 v29, 0xffff0000, v41
	v_lshlrev_b32_e32 v30, 16, v42
	v_and_b32_e32 v31, 0xffff0000, v42
	v_lshlrev_b32_e32 v32, 16, v43
	v_and_b32_e32 v33, 0xffff0000, v43
	global_store_dwordx4 v[36:37], v[0:3], off
	v_lshl_add_u64 v[36:37], v[36:37], 0, s[12:13]
	v_pk_fma_f32 v[12:13], v[12:13], v[104:105], v[26:27]
	v_pk_fma_f32 v[14:15], v[14:15], v[106:107], v[28:29]
	v_pk_fma_f32 v[16:17], v[16:17], v[170:171], v[30:31]
	v_pk_fma_f32 v[18:19], v[18:19], v[172:173], v[32:33]
	global_load_dwordx4 v[96:99], v[34:35], off
	global_load_dwordx4 v[162:165], v[38:39], off
	global_load_dwordx4 v[230:233], v[38:39], off offset:16
	v_lshl_add_u64 v[34:35], v[34:35], 0, s[12:13]
	v_lshl_add_u64 v[38:39], v[38:39], 0, s[14:15]
	s_waitcnt vmcnt(40)
	v_cvt_pk_bf16_f32 v22, v12, v13
	v_cvt_pk_bf16_f32 v23, v14, v15
	v_cvt_pk_bf16_f32 v24, v16, v17
	v_cvt_pk_bf16_f32 v25, v18, v19
	v_lshlrev_b32_e32 v26, 16, v44
	v_and_b32_e32 v27, 0xffff0000, v44
	v_lshlrev_b32_e32 v28, 16, v45
	v_and_b32_e32 v29, 0xffff0000, v45
	v_lshlrev_b32_e32 v30, 16, v46
	v_and_b32_e32 v31, 0xffff0000, v46
	v_lshlrev_b32_e32 v32, 16, v47
	v_and_b32_e32 v33, 0xffff0000, v47
	global_store_dwordx4 v[36:37], v[22:25], off
	v_lshl_add_u64 v[36:37], v[36:37], 0, s[12:13]
	v_pk_fma_f32 v[12:13], v[12:13], v[108:109], v[26:27]
	v_pk_fma_f32 v[14:15], v[14:15], v[110:111], v[28:29]
	v_pk_fma_f32 v[16:17], v[16:17], v[174:175], v[30:31]
	v_pk_fma_f32 v[18:19], v[18:19], v[176:177], v[32:33]
	global_load_dwordx4 v[100:103], v[34:35], off
	global_load_dwordx4 v[166:169], v[38:39], off
	global_load_dwordx4 v[234:237], v[38:39], off offset:16
	v_lshl_add_u64 v[34:35], v[34:35], 0, s[12:13]
	v_lshl_add_u64 v[38:39], v[38:39], 0, s[14:15]
	s_waitcnt vmcnt(41)
	v_cvt_pk_bf16_f32 v0, v12, v13
	v_cvt_pk_bf16_f32 v1, v14, v15
	v_cvt_pk_bf16_f32 v2, v16, v17
	v_cvt_pk_bf16_f32 v3, v18, v19
	v_lshlrev_b32_e32 v26, 16, v48
	v_and_b32_e32 v27, 0xffff0000, v48
	v_lshlrev_b32_e32 v28, 16, v49
	v_and_b32_e32 v29, 0xffff0000, v49
	v_lshlrev_b32_e32 v30, 16, v50
	v_and_b32_e32 v31, 0xffff0000, v50
	v_lshlrev_b32_e32 v32, 16, v51
	v_and_b32_e32 v33, 0xffff0000, v51
	global_store_dwordx4 v[36:37], v[0:3], off
	v_lshl_add_u64 v[36:37], v[36:37], 0, s[12:13]
	v_pk_fma_f32 v[12:13], v[12:13], v[112:113], v[26:27]
	v_pk_fma_f32 v[14:15], v[14:15], v[114:115], v[28:29]
	v_pk_fma_f32 v[16:17], v[16:17], v[178:179], v[30:31]
	v_pk_fma_f32 v[18:19], v[18:19], v[180:181], v[32:33]
	global_load_dwordx4 v[40:43], v[34:35], off
	global_load_dwordx4 v[104:107], v[38:39], off
	global_load_dwordx4 v[170:173], v[38:39], off offset:16
	v_lshl_add_u64 v[34:35], v[34:35], 0, s[12:13]
	v_lshl_add_u64 v[38:39], v[38:39], 0, s[14:15]
	s_waitcnt vmcnt(42)
	v_cvt_pk_bf16_f32 v22, v12, v13
	v_cvt_pk_bf16_f32 v23, v14, v15
	v_cvt_pk_bf16_f32 v24, v16, v17
	v_cvt_pk_bf16_f32 v25, v18, v19
	v_lshlrev_b32_e32 v26, 16, v52
	v_and_b32_e32 v27, 0xffff0000, v52
	v_lshlrev_b32_e32 v28, 16, v53
	v_and_b32_e32 v29, 0xffff0000, v53
	v_lshlrev_b32_e32 v30, 16, v54
	v_and_b32_e32 v31, 0xffff0000, v54
	v_lshlrev_b32_e32 v32, 16, v55
	v_and_b32_e32 v33, 0xffff0000, v55
	global_store_dwordx4 v[36:37], v[22:25], off
	v_lshl_add_u64 v[36:37], v[36:37], 0, s[12:13]
	v_pk_fma_f32 v[12:13], v[12:13], v[116:117], v[26:27]
	v_pk_fma_f32 v[14:15], v[14:15], v[118:119], v[28:29]
	v_pk_fma_f32 v[16:17], v[16:17], v[186:187], v[30:31]
	v_pk_fma_f32 v[18:19], v[18:19], v[188:189], v[32:33]
	global_load_dwordx4 v[44:47], v[34:35], off
	global_load_dwordx4 v[108:111], v[38:39], off
	global_load_dwordx4 v[174:177], v[38:39], off offset:16
	v_lshl_add_u64 v[34:35], v[34:35], 0, s[12:13]
	v_lshl_add_u64 v[38:39], v[38:39], 0, s[14:15]
	s_waitcnt vmcnt(43)
	v_cvt_pk_bf16_f32 v0, v12, v13
	v_cvt_pk_bf16_f32 v1, v14, v15
	v_cvt_pk_bf16_f32 v2, v16, v17
	v_cvt_pk_bf16_f32 v3, v18, v19
	v_lshlrev_b32_e32 v26, 16, v56
	v_and_b32_e32 v27, 0xffff0000, v56
	v_lshlrev_b32_e32 v28, 16, v57
	v_and_b32_e32 v29, 0xffff0000, v57
	v_lshlrev_b32_e32 v30, 16, v58
	v_and_b32_e32 v31, 0xffff0000, v58
	v_lshlrev_b32_e32 v32, 16, v59
	v_and_b32_e32 v33, 0xffff0000, v59
	global_store_dwordx4 v[36:37], v[0:3], off
	v_lshl_add_u64 v[36:37], v[36:37], 0, s[12:13]
	v_pk_fma_f32 v[12:13], v[12:13], v[120:121], v[26:27]
	v_pk_fma_f32 v[14:15], v[14:15], v[122:123], v[28:29]
	v_pk_fma_f32 v[16:17], v[16:17], v[190:191], v[30:31]
	v_pk_fma_f32 v[18:19], v[18:19], v[192:193], v[32:33]
	global_load_dwordx4 v[48:51], v[34:35], off
	global_load_dwordx4 v[112:115], v[38:39], off
	global_load_dwordx4 v[178:181], v[38:39], off offset:16
	v_lshl_add_u64 v[34:35], v[34:35], 0, s[12:13]
	v_lshl_add_u64 v[38:39], v[38:39], 0, s[14:15]
	s_waitcnt vmcnt(44)
	v_cvt_pk_bf16_f32 v22, v12, v13
	v_cvt_pk_bf16_f32 v23, v14, v15
	v_cvt_pk_bf16_f32 v24, v16, v17
	v_cvt_pk_bf16_f32 v25, v18, v19
	v_lshlrev_b32_e32 v26, 16, v60
	v_and_b32_e32 v27, 0xffff0000, v60
	v_lshlrev_b32_e32 v28, 16, v61
	v_and_b32_e32 v29, 0xffff0000, v61
	v_lshlrev_b32_e32 v30, 16, v62
	v_and_b32_e32 v31, 0xffff0000, v62
	v_lshlrev_b32_e32 v32, 16, v63
	v_and_b32_e32 v33, 0xffff0000, v63
	global_store_dwordx4 v[36:37], v[22:25], off
	v_lshl_add_u64 v[36:37], v[36:37], 0, s[12:13]
	v_pk_fma_f32 v[12:13], v[12:13], v[124:125], v[26:27]
	v_pk_fma_f32 v[14:15], v[14:15], v[126:127], v[28:29]
	v_pk_fma_f32 v[16:17], v[16:17], v[194:195], v[30:31]
	v_pk_fma_f32 v[18:19], v[18:19], v[196:197], v[32:33]
	global_load_dwordx4 v[52:55], v[34:35], off
	global_load_dwordx4 v[116:119], v[38:39], off
	global_load_dwordx4 v[186:189], v[38:39], off offset:16
	v_lshl_add_u64 v[34:35], v[34:35], 0, s[12:13]
	v_lshl_add_u64 v[38:39], v[38:39], 0, s[14:15]
	s_waitcnt vmcnt(45)
	v_cvt_pk_bf16_f32 v0, v12, v13
	v_cvt_pk_bf16_f32 v1, v14, v15
	v_cvt_pk_bf16_f32 v2, v16, v17
	v_cvt_pk_bf16_f32 v3, v18, v19
	v_lshlrev_b32_e32 v26, 16, v64
	v_and_b32_e32 v27, 0xffff0000, v64
	v_lshlrev_b32_e32 v28, 16, v65
	v_and_b32_e32 v29, 0xffff0000, v65
	v_lshlrev_b32_e32 v30, 16, v66
	v_and_b32_e32 v31, 0xffff0000, v66
	v_lshlrev_b32_e32 v32, 16, v67
	v_and_b32_e32 v33, 0xffff0000, v67
	global_store_dwordx4 v[36:37], v[0:3], off
	v_lshl_add_u64 v[36:37], v[36:37], 0, s[12:13]
	v_pk_fma_f32 v[12:13], v[12:13], v[128:129], v[26:27]
	v_pk_fma_f32 v[14:15], v[14:15], v[130:131], v[28:29]
	v_pk_fma_f32 v[16:17], v[16:17], v[198:199], v[30:31]
	v_pk_fma_f32 v[18:19], v[18:19], v[200:201], v[32:33]
	global_load_dwordx4 v[56:59], v[34:35], off
	global_load_dwordx4 v[120:123], v[38:39], off
	global_load_dwordx4 v[190:193], v[38:39], off offset:16
	v_lshl_add_u64 v[34:35], v[34:35], 0, s[12:13]
	v_lshl_add_u64 v[38:39], v[38:39], 0, s[14:15]
	s_waitcnt vmcnt(46)
	v_cvt_pk_bf16_f32 v22, v12, v13
	v_cvt_pk_bf16_f32 v23, v14, v15
	v_cvt_pk_bf16_f32 v24, v16, v17
	v_cvt_pk_bf16_f32 v25, v18, v19
	v_lshlrev_b32_e32 v26, 16, v68
	v_and_b32_e32 v27, 0xffff0000, v68
	v_lshlrev_b32_e32 v28, 16, v69
	v_and_b32_e32 v29, 0xffff0000, v69
	v_lshlrev_b32_e32 v30, 16, v70
	v_and_b32_e32 v31, 0xffff0000, v70
	v_lshlrev_b32_e32 v32, 16, v71
	v_and_b32_e32 v33, 0xffff0000, v71
	global_store_dwordx4 v[36:37], v[22:25], off
	v_lshl_add_u64 v[36:37], v[36:37], 0, s[12:13]
	v_pk_fma_f32 v[12:13], v[12:13], v[132:133], v[26:27]
	v_pk_fma_f32 v[14:15], v[14:15], v[134:135], v[28:29]
	v_pk_fma_f32 v[16:17], v[16:17], v[202:203], v[30:31]
	v_pk_fma_f32 v[18:19], v[18:19], v[204:205], v[32:33]
	global_load_dwordx4 v[60:63], v[34:35], off
	global_load_dwordx4 v[124:127], v[38:39], off
	global_load_dwordx4 v[194:197], v[38:39], off offset:16
	v_lshl_add_u64 v[34:35], v[34:35], 0, s[12:13]
	v_lshl_add_u64 v[38:39], v[38:39], 0, s[14:15]
	s_waitcnt vmcnt(47)
	v_cvt_pk_bf16_f32 v0, v12, v13
	v_cvt_pk_bf16_f32 v1, v14, v15
	v_cvt_pk_bf16_f32 v2, v16, v17
	v_cvt_pk_bf16_f32 v3, v18, v19
	v_lshlrev_b32_e32 v26, 16, v72
	v_and_b32_e32 v27, 0xffff0000, v72
	v_lshlrev_b32_e32 v28, 16, v73
	v_and_b32_e32 v29, 0xffff0000, v73
	v_lshlrev_b32_e32 v30, 16, v74
	v_and_b32_e32 v31, 0xffff0000, v74
	v_lshlrev_b32_e32 v32, 16, v75
	v_and_b32_e32 v33, 0xffff0000, v75
	global_store_dwordx4 v[36:37], v[0:3], off
	v_lshl_add_u64 v[36:37], v[36:37], 0, s[12:13]
	v_pk_fma_f32 v[12:13], v[12:13], v[136:137], v[26:27]
	v_pk_fma_f32 v[14:15], v[14:15], v[138:139], v[28:29]
	v_pk_fma_f32 v[16:17], v[16:17], v[206:207], v[30:31]
	v_pk_fma_f32 v[18:19], v[18:19], v[208:209], v[32:33]
	global_load_dwordx4 v[64:67], v[34:35], off
	global_load_dwordx4 v[128:131], v[38:39], off
	global_load_dwordx4 v[198:201], v[38:39], off offset:16
	v_lshl_add_u64 v[34:35], v[34:35], 0, s[12:13]
	v_lshl_add_u64 v[38:39], v[38:39], 0, s[14:15]
	s_waitcnt vmcnt(48)
	v_cvt_pk_bf16_f32 v22, v12, v13
	v_cvt_pk_bf16_f32 v23, v14, v15
	v_cvt_pk_bf16_f32 v24, v16, v17
	v_cvt_pk_bf16_f32 v25, v18, v19
	v_lshlrev_b32_e32 v26, 16, v76
	v_and_b32_e32 v27, 0xffff0000, v76
	v_lshlrev_b32_e32 v28, 16, v77
	v_and_b32_e32 v29, 0xffff0000, v77
	v_lshlrev_b32_e32 v30, 16, v78
	v_and_b32_e32 v31, 0xffff0000, v78
	v_lshlrev_b32_e32 v32, 16, v79
	v_and_b32_e32 v33, 0xffff0000, v79
	global_store_dwordx4 v[36:37], v[22:25], off
	v_lshl_add_u64 v[36:37], v[36:37], 0, s[12:13]
	v_pk_fma_f32 v[12:13], v[12:13], v[140:141], v[26:27]
	v_pk_fma_f32 v[14:15], v[14:15], v[142:143], v[28:29]
	v_pk_fma_f32 v[16:17], v[16:17], v[210:211], v[30:31]
	v_pk_fma_f32 v[18:19], v[18:19], v[212:213], v[32:33]
	global_load_dwordx4 v[68:71], v[34:35], off
	global_load_dwordx4 v[132:135], v[38:39], off
	global_load_dwordx4 v[202:205], v[38:39], off offset:16
	v_lshl_add_u64 v[34:35], v[34:35], 0, s[12:13]
	v_lshl_add_u64 v[38:39], v[38:39], 0, s[14:15]
	s_waitcnt vmcnt(49)
	v_cvt_pk_bf16_f32 v0, v12, v13
	v_cvt_pk_bf16_f32 v1, v14, v15
	v_cvt_pk_bf16_f32 v2, v16, v17
	v_cvt_pk_bf16_f32 v3, v18, v19
	v_lshlrev_b32_e32 v26, 16, v80
	v_and_b32_e32 v27, 0xffff0000, v80
	v_lshlrev_b32_e32 v28, 16, v81
	v_and_b32_e32 v29, 0xffff0000, v81
	v_lshlrev_b32_e32 v30, 16, v82
	v_and_b32_e32 v31, 0xffff0000, v82
	v_lshlrev_b32_e32 v32, 16, v83
	v_and_b32_e32 v33, 0xffff0000, v83
	global_store_dwordx4 v[36:37], v[0:3], off
	v_lshl_add_u64 v[36:37], v[36:37], 0, s[12:13]
	v_pk_fma_f32 v[12:13], v[12:13], v[146:147], v[26:27]
	v_pk_fma_f32 v[14:15], v[14:15], v[148:149], v[28:29]
	v_pk_fma_f32 v[16:17], v[16:17], v[214:215], v[30:31]
	v_pk_fma_f32 v[18:19], v[18:19], v[216:217], v[32:33]
	global_load_dwordx4 v[72:75], v[34:35], off
	global_load_dwordx4 v[136:139], v[38:39], off
	global_load_dwordx4 v[206:209], v[38:39], off offset:16
	v_lshl_add_u64 v[34:35], v[34:35], 0, s[12:13]
	v_lshl_add_u64 v[38:39], v[38:39], 0, s[14:15]
	s_waitcnt vmcnt(50)
	v_cvt_pk_bf16_f32 v22, v12, v13
	v_cvt_pk_bf16_f32 v23, v14, v15
	v_cvt_pk_bf16_f32 v24, v16, v17
	v_cvt_pk_bf16_f32 v25, v18, v19
	v_lshlrev_b32_e32 v26, 16, v84
	v_and_b32_e32 v27, 0xffff0000, v84
	v_lshlrev_b32_e32 v28, 16, v85
	v_and_b32_e32 v29, 0xffff0000, v85
	v_lshlrev_b32_e32 v30, 16, v86
	v_and_b32_e32 v31, 0xffff0000, v86
	v_lshlrev_b32_e32 v32, 16, v87
	v_and_b32_e32 v33, 0xffff0000, v87
	global_store_dwordx4 v[36:37], v[22:25], off
	v_lshl_add_u64 v[36:37], v[36:37], 0, s[12:13]
	v_pk_fma_f32 v[12:13], v[12:13], v[150:151], v[26:27]
	v_pk_fma_f32 v[14:15], v[14:15], v[152:153], v[28:29]
	v_pk_fma_f32 v[16:17], v[16:17], v[218:219], v[30:31]
	v_pk_fma_f32 v[18:19], v[18:19], v[220:221], v[32:33]
	global_load_dwordx4 v[76:79], v[34:35], off
	global_load_dwordx4 v[140:143], v[38:39], off
	global_load_dwordx4 v[210:213], v[38:39], off offset:16
	v_lshl_add_u64 v[34:35], v[34:35], 0, s[12:13]
	v_lshl_add_u64 v[38:39], v[38:39], 0, s[14:15]
	s_waitcnt vmcnt(51)
	v_cvt_pk_bf16_f32 v0, v12, v13
	v_cvt_pk_bf16_f32 v1, v14, v15
	v_cvt_pk_bf16_f32 v2, v16, v17
	v_cvt_pk_bf16_f32 v3, v18, v19
	v_lshlrev_b32_e32 v26, 16, v88
	v_and_b32_e32 v27, 0xffff0000, v88
	v_lshlrev_b32_e32 v28, 16, v89
	v_and_b32_e32 v29, 0xffff0000, v89
	v_lshlrev_b32_e32 v30, 16, v90
	v_and_b32_e32 v31, 0xffff0000, v90
	v_lshlrev_b32_e32 v32, 16, v91
	v_and_b32_e32 v33, 0xffff0000, v91
	global_store_dwordx4 v[36:37], v[0:3], off
	v_lshl_add_u64 v[36:37], v[36:37], 0, s[12:13]
	v_pk_fma_f32 v[12:13], v[12:13], v[154:155], v[26:27]
	v_pk_fma_f32 v[14:15], v[14:15], v[156:157], v[28:29]
	v_pk_fma_f32 v[16:17], v[16:17], v[222:223], v[30:31]
	v_pk_fma_f32 v[18:19], v[18:19], v[224:225], v[32:33]
	global_load_dwordx4 v[80:83], v[34:35], off
	global_load_dwordx4 v[146:149], v[38:39], off
	global_load_dwordx4 v[214:217], v[38:39], off offset:16
	v_lshl_add_u64 v[34:35], v[34:35], 0, s[12:13]
	v_lshl_add_u64 v[38:39], v[38:39], 0, s[14:15]
	s_waitcnt vmcnt(52)
	v_cvt_pk_bf16_f32 v22, v12, v13
	v_cvt_pk_bf16_f32 v23, v14, v15
	v_cvt_pk_bf16_f32 v24, v16, v17
	v_cvt_pk_bf16_f32 v25, v18, v19
	v_lshlrev_b32_e32 v26, 16, v92
	v_and_b32_e32 v27, 0xffff0000, v92
	v_lshlrev_b32_e32 v28, 16, v93
	v_and_b32_e32 v29, 0xffff0000, v93
	v_lshlrev_b32_e32 v30, 16, v94
	v_and_b32_e32 v31, 0xffff0000, v94
	v_lshlrev_b32_e32 v32, 16, v95
	v_and_b32_e32 v33, 0xffff0000, v95
	global_store_dwordx4 v[36:37], v[22:25], off
	v_lshl_add_u64 v[36:37], v[36:37], 0, s[12:13]
	v_pk_fma_f32 v[12:13], v[12:13], v[158:159], v[26:27]
	v_pk_fma_f32 v[14:15], v[14:15], v[160:161], v[28:29]
	v_pk_fma_f32 v[16:17], v[16:17], v[226:227], v[30:31]
	v_pk_fma_f32 v[18:19], v[18:19], v[228:229], v[32:33]
	global_load_dwordx4 v[84:87], v[34:35], off
	global_load_dwordx4 v[150:153], v[38:39], off
	global_load_dwordx4 v[218:221], v[38:39], off offset:16
	v_lshl_add_u64 v[34:35], v[34:35], 0, s[12:13]
	v_lshl_add_u64 v[38:39], v[38:39], 0, s[14:15]
	s_waitcnt vmcnt(52)
	v_cvt_pk_bf16_f32 v0, v12, v13
	v_cvt_pk_bf16_f32 v1, v14, v15
	v_cvt_pk_bf16_f32 v2, v16, v17
	v_cvt_pk_bf16_f32 v3, v18, v19
	v_lshlrev_b32_e32 v26, 16, v96
	v_and_b32_e32 v27, 0xffff0000, v96
	v_lshlrev_b32_e32 v28, 16, v97
	v_and_b32_e32 v29, 0xffff0000, v97
	v_lshlrev_b32_e32 v30, 16, v98
	v_and_b32_e32 v31, 0xffff0000, v98
	v_lshlrev_b32_e32 v32, 16, v99
	v_and_b32_e32 v33, 0xffff0000, v99
	global_store_dwordx4 v[36:37], v[0:3], off
	v_lshl_add_u64 v[36:37], v[36:37], 0, s[12:13]
	v_pk_fma_f32 v[12:13], v[12:13], v[162:163], v[26:27]
	v_pk_fma_f32 v[14:15], v[14:15], v[164:165], v[28:29]
	v_pk_fma_f32 v[16:17], v[16:17], v[230:231], v[30:31]
	v_pk_fma_f32 v[18:19], v[18:19], v[232:233], v[32:33]
	global_load_dwordx4 v[88:91], v[34:35], off
	global_load_dwordx4 v[154:157], v[38:39], off
	global_load_dwordx4 v[222:225], v[38:39], off offset:16
	v_lshl_add_u64 v[34:35], v[34:35], 0, s[12:13]
	v_lshl_add_u64 v[38:39], v[38:39], 0, s[14:15]
	s_waitcnt vmcnt(52)
	v_cvt_pk_bf16_f32 v22, v12, v13
	v_cvt_pk_bf16_f32 v23, v14, v15
	v_cvt_pk_bf16_f32 v24, v16, v17
	v_cvt_pk_bf16_f32 v25, v18, v19
	v_lshlrev_b32_e32 v26, 16, v100
	v_and_b32_e32 v27, 0xffff0000, v100
	v_lshlrev_b32_e32 v28, 16, v101
	v_and_b32_e32 v29, 0xffff0000, v101
	v_lshlrev_b32_e32 v30, 16, v102
	v_and_b32_e32 v31, 0xffff0000, v102
	v_lshlrev_b32_e32 v32, 16, v103
	v_and_b32_e32 v33, 0xffff0000, v103
	global_store_dwordx4 v[36:37], v[22:25], off
	v_lshl_add_u64 v[36:37], v[36:37], 0, s[12:13]
	v_pk_fma_f32 v[12:13], v[12:13], v[166:167], v[26:27]
	v_pk_fma_f32 v[14:15], v[14:15], v[168:169], v[28:29]
	v_pk_fma_f32 v[16:17], v[16:17], v[234:235], v[30:31]
	v_pk_fma_f32 v[18:19], v[18:19], v[236:237], v[32:33]
	global_load_dwordx4 v[92:95], v[34:35], off
	global_load_dwordx4 v[158:161], v[38:39], off
	global_load_dwordx4 v[226:229], v[38:39], off offset:16
	v_lshl_add_u64 v[34:35], v[34:35], 0, s[12:13]
	v_lshl_add_u64 v[38:39], v[38:39], 0, s[14:15]
	s_waitcnt vmcnt(52)
	v_cvt_pk_bf16_f32 v0, v12, v13
	v_cvt_pk_bf16_f32 v1, v14, v15
	v_cvt_pk_bf16_f32 v2, v16, v17
	v_cvt_pk_bf16_f32 v3, v18, v19
	v_lshlrev_b32_e32 v26, 16, v40
	v_and_b32_e32 v27, 0xffff0000, v40
	v_lshlrev_b32_e32 v28, 16, v41
	v_and_b32_e32 v29, 0xffff0000, v41
	v_lshlrev_b32_e32 v30, 16, v42
	v_and_b32_e32 v31, 0xffff0000, v42
	v_lshlrev_b32_e32 v32, 16, v43
	v_and_b32_e32 v33, 0xffff0000, v43
	global_store_dwordx4 v[36:37], v[0:3], off
	v_lshl_add_u64 v[36:37], v[36:37], 0, s[12:13]
	v_pk_fma_f32 v[12:13], v[12:13], v[104:105], v[26:27]
	v_pk_fma_f32 v[14:15], v[14:15], v[106:107], v[28:29]
	v_pk_fma_f32 v[16:17], v[16:17], v[170:171], v[30:31]
	v_pk_fma_f32 v[18:19], v[18:19], v[172:173], v[32:33]
	global_load_dwordx4 v[96:99], v[34:35], off
	global_load_dwordx4 v[162:165], v[38:39], off
	global_load_dwordx4 v[230:233], v[38:39], off offset:16
	v_lshl_add_u64 v[34:35], v[34:35], 0, s[12:13]
	v_lshl_add_u64 v[38:39], v[38:39], 0, s[14:15]
	s_waitcnt vmcnt(52)
	v_cvt_pk_bf16_f32 v22, v12, v13
	v_cvt_pk_bf16_f32 v23, v14, v15
	v_cvt_pk_bf16_f32 v24, v16, v17
	v_cvt_pk_bf16_f32 v25, v18, v19
	v_lshlrev_b32_e32 v26, 16, v44
	v_and_b32_e32 v27, 0xffff0000, v44
	v_lshlrev_b32_e32 v28, 16, v45
	v_and_b32_e32 v29, 0xffff0000, v45
	v_lshlrev_b32_e32 v30, 16, v46
	v_and_b32_e32 v31, 0xffff0000, v46
	v_lshlrev_b32_e32 v32, 16, v47
	v_and_b32_e32 v33, 0xffff0000, v47
	global_store_dwordx4 v[36:37], v[22:25], off
	v_lshl_add_u64 v[36:37], v[36:37], 0, s[12:13]
	v_pk_fma_f32 v[12:13], v[12:13], v[108:109], v[26:27]
	v_pk_fma_f32 v[14:15], v[14:15], v[110:111], v[28:29]
	v_pk_fma_f32 v[16:17], v[16:17], v[174:175], v[30:31]
	v_pk_fma_f32 v[18:19], v[18:19], v[176:177], v[32:33]
	global_load_dwordx4 v[100:103], v[34:35], off
	global_load_dwordx4 v[166:169], v[38:39], off
	global_load_dwordx4 v[234:237], v[38:39], off offset:16
	v_lshl_add_u64 v[34:35], v[34:35], 0, s[12:13]
	v_lshl_add_u64 v[38:39], v[38:39], 0, s[14:15]
	s_waitcnt vmcnt(52)
	v_cvt_pk_bf16_f32 v0, v12, v13
	v_cvt_pk_bf16_f32 v1, v14, v15
	v_cvt_pk_bf16_f32 v2, v16, v17
	v_cvt_pk_bf16_f32 v3, v18, v19
	v_lshlrev_b32_e32 v26, 16, v48
	v_and_b32_e32 v27, 0xffff0000, v48
	v_lshlrev_b32_e32 v28, 16, v49
	v_and_b32_e32 v29, 0xffff0000, v49
	v_lshlrev_b32_e32 v30, 16, v50
	v_and_b32_e32 v31, 0xffff0000, v50
	v_lshlrev_b32_e32 v32, 16, v51
	v_and_b32_e32 v33, 0xffff0000, v51
	global_store_dwordx4 v[36:37], v[0:3], off
	v_lshl_add_u64 v[36:37], v[36:37], 0, s[12:13]
	v_pk_fma_f32 v[12:13], v[12:13], v[112:113], v[26:27]
	v_pk_fma_f32 v[14:15], v[14:15], v[114:115], v[28:29]
	v_pk_fma_f32 v[16:17], v[16:17], v[178:179], v[30:31]
	v_pk_fma_f32 v[18:19], v[18:19], v[180:181], v[32:33]
	global_load_dwordx4 v[40:43], v[34:35], off
	global_load_dwordx4 v[104:107], v[38:39], off
	global_load_dwordx4 v[170:173], v[38:39], off offset:16
	v_lshl_add_u64 v[34:35], v[34:35], 0, s[12:13]
	v_lshl_add_u64 v[38:39], v[38:39], 0, s[14:15]
	s_waitcnt vmcnt(52)
	v_cvt_pk_bf16_f32 v22, v12, v13
	v_cvt_pk_bf16_f32 v23, v14, v15
	v_cvt_pk_bf16_f32 v24, v16, v17
	v_cvt_pk_bf16_f32 v25, v18, v19
	v_lshlrev_b32_e32 v26, 16, v52
	v_and_b32_e32 v27, 0xffff0000, v52
	v_lshlrev_b32_e32 v28, 16, v53
	v_and_b32_e32 v29, 0xffff0000, v53
	v_lshlrev_b32_e32 v30, 16, v54
	v_and_b32_e32 v31, 0xffff0000, v54
	v_lshlrev_b32_e32 v32, 16, v55
	v_and_b32_e32 v33, 0xffff0000, v55
	global_store_dwordx4 v[36:37], v[22:25], off
	v_lshl_add_u64 v[36:37], v[36:37], 0, s[12:13]
	v_pk_fma_f32 v[12:13], v[12:13], v[116:117], v[26:27]
	v_pk_fma_f32 v[14:15], v[14:15], v[118:119], v[28:29]
	v_pk_fma_f32 v[16:17], v[16:17], v[186:187], v[30:31]
	v_pk_fma_f32 v[18:19], v[18:19], v[188:189], v[32:33]
	global_load_dwordx4 v[44:47], v[34:35], off
	global_load_dwordx4 v[108:111], v[38:39], off
	global_load_dwordx4 v[174:177], v[38:39], off offset:16
	v_lshl_add_u64 v[34:35], v[34:35], 0, s[12:13]
	v_lshl_add_u64 v[38:39], v[38:39], 0, s[14:15]
	s_waitcnt vmcnt(52)
	v_cvt_pk_bf16_f32 v0, v12, v13
	v_cvt_pk_bf16_f32 v1, v14, v15
	v_cvt_pk_bf16_f32 v2, v16, v17
	v_cvt_pk_bf16_f32 v3, v18, v19
	v_lshlrev_b32_e32 v26, 16, v56
	v_and_b32_e32 v27, 0xffff0000, v56
	v_lshlrev_b32_e32 v28, 16, v57
	v_and_b32_e32 v29, 0xffff0000, v57
	v_lshlrev_b32_e32 v30, 16, v58
	v_and_b32_e32 v31, 0xffff0000, v58
	v_lshlrev_b32_e32 v32, 16, v59
	v_and_b32_e32 v33, 0xffff0000, v59
	global_store_dwordx4 v[36:37], v[0:3], off
	v_lshl_add_u64 v[36:37], v[36:37], 0, s[12:13]
	v_pk_fma_f32 v[12:13], v[12:13], v[120:121], v[26:27]
	v_pk_fma_f32 v[14:15], v[14:15], v[122:123], v[28:29]
	v_pk_fma_f32 v[16:17], v[16:17], v[190:191], v[30:31]
	v_pk_fma_f32 v[18:19], v[18:19], v[192:193], v[32:33]
	global_load_dwordx4 v[48:51], v[34:35], off
	global_load_dwordx4 v[112:115], v[38:39], off
	global_load_dwordx4 v[178:181], v[38:39], off offset:16
	v_lshl_add_u64 v[34:35], v[34:35], 0, s[12:13]
	v_lshl_add_u64 v[38:39], v[38:39], 0, s[14:15]
	s_waitcnt vmcnt(52)
	v_cvt_pk_bf16_f32 v22, v12, v13
	v_cvt_pk_bf16_f32 v23, v14, v15
	v_cvt_pk_bf16_f32 v24, v16, v17
	v_cvt_pk_bf16_f32 v25, v18, v19
	v_lshlrev_b32_e32 v26, 16, v60
	v_and_b32_e32 v27, 0xffff0000, v60
	v_lshlrev_b32_e32 v28, 16, v61
	v_and_b32_e32 v29, 0xffff0000, v61
	v_lshlrev_b32_e32 v30, 16, v62
	v_and_b32_e32 v31, 0xffff0000, v62
	v_lshlrev_b32_e32 v32, 16, v63
	v_and_b32_e32 v33, 0xffff0000, v63
	global_store_dwordx4 v[36:37], v[22:25], off
	v_lshl_add_u64 v[36:37], v[36:37], 0, s[12:13]
	v_pk_fma_f32 v[12:13], v[12:13], v[124:125], v[26:27]
	v_pk_fma_f32 v[14:15], v[14:15], v[126:127], v[28:29]
	v_pk_fma_f32 v[16:17], v[16:17], v[194:195], v[30:31]
	v_pk_fma_f32 v[18:19], v[18:19], v[196:197], v[32:33]
	global_load_dwordx4 v[52:55], v[34:35], off
	global_load_dwordx4 v[116:119], v[38:39], off
	global_load_dwordx4 v[186:189], v[38:39], off offset:16
	v_lshl_add_u64 v[34:35], v[34:35], 0, s[12:13]
	v_lshl_add_u64 v[38:39], v[38:39], 0, s[14:15]
	s_waitcnt vmcnt(52)
	v_cvt_pk_bf16_f32 v0, v12, v13
	v_cvt_pk_bf16_f32 v1, v14, v15
	v_cvt_pk_bf16_f32 v2, v16, v17
	v_cvt_pk_bf16_f32 v3, v18, v19
	v_lshlrev_b32_e32 v26, 16, v64
	v_and_b32_e32 v27, 0xffff0000, v64
	v_lshlrev_b32_e32 v28, 16, v65
	v_and_b32_e32 v29, 0xffff0000, v65
	v_lshlrev_b32_e32 v30, 16, v66
	v_and_b32_e32 v31, 0xffff0000, v66
	v_lshlrev_b32_e32 v32, 16, v67
	v_and_b32_e32 v33, 0xffff0000, v67
	global_store_dwordx4 v[36:37], v[0:3], off
	v_lshl_add_u64 v[36:37], v[36:37], 0, s[12:13]
	v_pk_fma_f32 v[12:13], v[12:13], v[128:129], v[26:27]
	v_pk_fma_f32 v[14:15], v[14:15], v[130:131], v[28:29]
	v_pk_fma_f32 v[16:17], v[16:17], v[198:199], v[30:31]
	v_pk_fma_f32 v[18:19], v[18:19], v[200:201], v[32:33]
	global_load_dwordx4 v[56:59], v[34:35], off
	global_load_dwordx4 v[120:123], v[38:39], off
	global_load_dwordx4 v[190:193], v[38:39], off offset:16
	v_lshl_add_u64 v[34:35], v[34:35], 0, s[12:13]
	v_lshl_add_u64 v[38:39], v[38:39], 0, s[14:15]
	s_waitcnt vmcnt(52)
	v_cvt_pk_bf16_f32 v22, v12, v13
	v_cvt_pk_bf16_f32 v23, v14, v15
	v_cvt_pk_bf16_f32 v24, v16, v17
	v_cvt_pk_bf16_f32 v25, v18, v19
	v_lshlrev_b32_e32 v26, 16, v68
	v_and_b32_e32 v27, 0xffff0000, v68
	v_lshlrev_b32_e32 v28, 16, v69
	v_and_b32_e32 v29, 0xffff0000, v69
	v_lshlrev_b32_e32 v30, 16, v70
	v_and_b32_e32 v31, 0xffff0000, v70
	v_lshlrev_b32_e32 v32, 16, v71
	v_and_b32_e32 v33, 0xffff0000, v71
	global_store_dwordx4 v[36:37], v[22:25], off
	v_lshl_add_u64 v[36:37], v[36:37], 0, s[12:13]
	v_pk_fma_f32 v[12:13], v[12:13], v[132:133], v[26:27]
	v_pk_fma_f32 v[14:15], v[14:15], v[134:135], v[28:29]
	v_pk_fma_f32 v[16:17], v[16:17], v[202:203], v[30:31]
	v_pk_fma_f32 v[18:19], v[18:19], v[204:205], v[32:33]
	global_load_dwordx4 v[60:63], v[34:35], off
	global_load_dwordx4 v[124:127], v[38:39], off
	global_load_dwordx4 v[194:197], v[38:39], off offset:16
	v_lshl_add_u64 v[34:35], v[34:35], 0, s[12:13]
	v_lshl_add_u64 v[38:39], v[38:39], 0, s[14:15]
	s_waitcnt vmcnt(52)
	v_cvt_pk_bf16_f32 v0, v12, v13
	v_cvt_pk_bf16_f32 v1, v14, v15
	v_cvt_pk_bf16_f32 v2, v16, v17
	v_cvt_pk_bf16_f32 v3, v18, v19
	v_lshlrev_b32_e32 v26, 16, v72
	v_and_b32_e32 v27, 0xffff0000, v72
	v_lshlrev_b32_e32 v28, 16, v73
	v_and_b32_e32 v29, 0xffff0000, v73
	v_lshlrev_b32_e32 v30, 16, v74
	v_and_b32_e32 v31, 0xffff0000, v74
	v_lshlrev_b32_e32 v32, 16, v75
	v_and_b32_e32 v33, 0xffff0000, v75
	global_store_dwordx4 v[36:37], v[0:3], off
	v_lshl_add_u64 v[36:37], v[36:37], 0, s[12:13]
	v_pk_fma_f32 v[12:13], v[12:13], v[136:137], v[26:27]
	v_pk_fma_f32 v[14:15], v[14:15], v[138:139], v[28:29]
	v_pk_fma_f32 v[16:17], v[16:17], v[206:207], v[30:31]
	v_pk_fma_f32 v[18:19], v[18:19], v[208:209], v[32:33]
	global_load_dwordx4 v[64:67], v[34:35], off
	global_load_dwordx4 v[128:131], v[38:39], off
	global_load_dwordx4 v[198:201], v[38:39], off offset:16
	v_lshl_add_u64 v[34:35], v[34:35], 0, s[12:13]
	v_lshl_add_u64 v[38:39], v[38:39], 0, s[14:15]
	s_waitcnt vmcnt(52)
	v_cvt_pk_bf16_f32 v22, v12, v13
	v_cvt_pk_bf16_f32 v23, v14, v15
	v_cvt_pk_bf16_f32 v24, v16, v17
	v_cvt_pk_bf16_f32 v25, v18, v19
	v_lshlrev_b32_e32 v26, 16, v76
	v_and_b32_e32 v27, 0xffff0000, v76
	v_lshlrev_b32_e32 v28, 16, v77
	v_and_b32_e32 v29, 0xffff0000, v77
	v_lshlrev_b32_e32 v30, 16, v78
	v_and_b32_e32 v31, 0xffff0000, v78
	v_lshlrev_b32_e32 v32, 16, v79
	v_and_b32_e32 v33, 0xffff0000, v79
	global_store_dwordx4 v[36:37], v[22:25], off
	v_lshl_add_u64 v[36:37], v[36:37], 0, s[12:13]
	v_pk_fma_f32 v[12:13], v[12:13], v[140:141], v[26:27]
	v_pk_fma_f32 v[14:15], v[14:15], v[142:143], v[28:29]
	v_pk_fma_f32 v[16:17], v[16:17], v[210:211], v[30:31]
	v_pk_fma_f32 v[18:19], v[18:19], v[212:213], v[32:33]
	global_load_dwordx4 v[68:71], v[34:35], off
	global_load_dwordx4 v[132:135], v[38:39], off
	global_load_dwordx4 v[202:205], v[38:39], off offset:16
	v_lshl_add_u64 v[34:35], v[34:35], 0, s[12:13]
	v_lshl_add_u64 v[38:39], v[38:39], 0, s[14:15]
	s_waitcnt vmcnt(52)
	v_cvt_pk_bf16_f32 v0, v12, v13
	v_cvt_pk_bf16_f32 v1, v14, v15
	v_cvt_pk_bf16_f32 v2, v16, v17
	v_cvt_pk_bf16_f32 v3, v18, v19
	v_lshlrev_b32_e32 v26, 16, v80
	v_and_b32_e32 v27, 0xffff0000, v80
	v_lshlrev_b32_e32 v28, 16, v81
	v_and_b32_e32 v29, 0xffff0000, v81
	v_lshlrev_b32_e32 v30, 16, v82
	v_and_b32_e32 v31, 0xffff0000, v82
	v_lshlrev_b32_e32 v32, 16, v83
	v_and_b32_e32 v33, 0xffff0000, v83
	global_store_dwordx4 v[36:37], v[0:3], off
	v_lshl_add_u64 v[36:37], v[36:37], 0, s[12:13]
	v_pk_fma_f32 v[12:13], v[12:13], v[146:147], v[26:27]
	v_pk_fma_f32 v[14:15], v[14:15], v[148:149], v[28:29]
	v_pk_fma_f32 v[16:17], v[16:17], v[214:215], v[30:31]
	v_pk_fma_f32 v[18:19], v[18:19], v[216:217], v[32:33]
	global_load_dwordx4 v[72:75], v[34:35], off
	global_load_dwordx4 v[136:139], v[38:39], off
	global_load_dwordx4 v[206:209], v[38:39], off offset:16
	v_lshl_add_u64 v[34:35], v[34:35], 0, s[12:13]
	v_lshl_add_u64 v[38:39], v[38:39], 0, s[14:15]
	s_waitcnt vmcnt(52)
	v_cvt_pk_bf16_f32 v22, v12, v13
	v_cvt_pk_bf16_f32 v23, v14, v15
	v_cvt_pk_bf16_f32 v24, v16, v17
	v_cvt_pk_bf16_f32 v25, v18, v19
	v_lshlrev_b32_e32 v26, 16, v84
	v_and_b32_e32 v27, 0xffff0000, v84
	v_lshlrev_b32_e32 v28, 16, v85
	v_and_b32_e32 v29, 0xffff0000, v85
	v_lshlrev_b32_e32 v30, 16, v86
	v_and_b32_e32 v31, 0xffff0000, v86
	v_lshlrev_b32_e32 v32, 16, v87
	v_and_b32_e32 v33, 0xffff0000, v87
	global_store_dwordx4 v[36:37], v[22:25], off
	v_lshl_add_u64 v[36:37], v[36:37], 0, s[12:13]
	v_pk_fma_f32 v[12:13], v[12:13], v[150:151], v[26:27]
	v_pk_fma_f32 v[14:15], v[14:15], v[152:153], v[28:29]
	v_pk_fma_f32 v[16:17], v[16:17], v[218:219], v[30:31]
	v_pk_fma_f32 v[18:19], v[18:19], v[220:221], v[32:33]
	global_load_dwordx4 v[76:79], v[34:35], off
	global_load_dwordx4 v[140:143], v[38:39], off
	global_load_dwordx4 v[210:213], v[38:39], off offset:16
	v_lshl_add_u64 v[34:35], v[34:35], 0, s[12:13]
	v_lshl_add_u64 v[38:39], v[38:39], 0, s[14:15]
	s_waitcnt vmcnt(52)
	v_cvt_pk_bf16_f32 v0, v12, v13
	v_cvt_pk_bf16_f32 v1, v14, v15
	v_cvt_pk_bf16_f32 v2, v16, v17
	v_cvt_pk_bf16_f32 v3, v18, v19
	v_lshlrev_b32_e32 v26, 16, v88
	v_and_b32_e32 v27, 0xffff0000, v88
	v_lshlrev_b32_e32 v28, 16, v89
	v_and_b32_e32 v29, 0xffff0000, v89
	v_lshlrev_b32_e32 v30, 16, v90
	v_and_b32_e32 v31, 0xffff0000, v90
	v_lshlrev_b32_e32 v32, 16, v91
	v_and_b32_e32 v33, 0xffff0000, v91
	global_store_dwordx4 v[36:37], v[0:3], off
	v_lshl_add_u64 v[36:37], v[36:37], 0, s[12:13]
	v_pk_fma_f32 v[12:13], v[12:13], v[154:155], v[26:27]
	v_pk_fma_f32 v[14:15], v[14:15], v[156:157], v[28:29]
	v_pk_fma_f32 v[16:17], v[16:17], v[222:223], v[30:31]
	v_pk_fma_f32 v[18:19], v[18:19], v[224:225], v[32:33]
	global_load_dwordx4 v[80:83], v[34:35], off
	global_load_dwordx4 v[146:149], v[38:39], off
	global_load_dwordx4 v[214:217], v[38:39], off offset:16
	v_lshl_add_u64 v[34:35], v[34:35], 0, s[12:13]
	v_lshl_add_u64 v[38:39], v[38:39], 0, s[14:15]
	s_waitcnt vmcnt(52)
	v_cvt_pk_bf16_f32 v22, v12, v13
	v_cvt_pk_bf16_f32 v23, v14, v15
	v_cvt_pk_bf16_f32 v24, v16, v17
	v_cvt_pk_bf16_f32 v25, v18, v19
	v_lshlrev_b32_e32 v26, 16, v92
	v_and_b32_e32 v27, 0xffff0000, v92
	v_lshlrev_b32_e32 v28, 16, v93
	v_and_b32_e32 v29, 0xffff0000, v93
	v_lshlrev_b32_e32 v30, 16, v94
	v_and_b32_e32 v31, 0xffff0000, v94
	v_lshlrev_b32_e32 v32, 16, v95
	v_and_b32_e32 v33, 0xffff0000, v95
	global_store_dwordx4 v[36:37], v[22:25], off
	v_lshl_add_u64 v[36:37], v[36:37], 0, s[12:13]
	v_pk_fma_f32 v[12:13], v[12:13], v[158:159], v[26:27]
	v_pk_fma_f32 v[14:15], v[14:15], v[160:161], v[28:29]
	v_pk_fma_f32 v[16:17], v[16:17], v[226:227], v[30:31]
	v_pk_fma_f32 v[18:19], v[18:19], v[228:229], v[32:33]
	global_load_dwordx4 v[84:87], v[34:35], off
	global_load_dwordx4 v[150:153], v[38:39], off
	global_load_dwordx4 v[218:221], v[38:39], off offset:16
	v_lshl_add_u64 v[34:35], v[34:35], 0, s[12:13]
	v_lshl_add_u64 v[38:39], v[38:39], 0, s[14:15]
	s_waitcnt vmcnt(52)
	v_cvt_pk_bf16_f32 v0, v12, v13
	v_cvt_pk_bf16_f32 v1, v14, v15
	v_cvt_pk_bf16_f32 v2, v16, v17
	v_cvt_pk_bf16_f32 v3, v18, v19
	v_lshlrev_b32_e32 v26, 16, v96
	v_and_b32_e32 v27, 0xffff0000, v96
	v_lshlrev_b32_e32 v28, 16, v97
	v_and_b32_e32 v29, 0xffff0000, v97
	v_lshlrev_b32_e32 v30, 16, v98
	v_and_b32_e32 v31, 0xffff0000, v98
	v_lshlrev_b32_e32 v32, 16, v99
	v_and_b32_e32 v33, 0xffff0000, v99
	global_store_dwordx4 v[36:37], v[0:3], off
	v_lshl_add_u64 v[36:37], v[36:37], 0, s[12:13]
	v_pk_fma_f32 v[12:13], v[12:13], v[162:163], v[26:27]
	v_pk_fma_f32 v[14:15], v[14:15], v[164:165], v[28:29]
	v_pk_fma_f32 v[16:17], v[16:17], v[230:231], v[30:31]
	v_pk_fma_f32 v[18:19], v[18:19], v[232:233], v[32:33]
	global_load_dwordx4 v[88:91], v[34:35], off
	global_load_dwordx4 v[154:157], v[38:39], off
	global_load_dwordx4 v[222:225], v[38:39], off offset:16
	v_lshl_add_u64 v[34:35], v[34:35], 0, s[12:13]
	v_lshl_add_u64 v[38:39], v[38:39], 0, s[14:15]
	s_waitcnt vmcnt(52)
	v_cvt_pk_bf16_f32 v22, v12, v13
	v_cvt_pk_bf16_f32 v23, v14, v15
	v_cvt_pk_bf16_f32 v24, v16, v17
	v_cvt_pk_bf16_f32 v25, v18, v19
	v_lshlrev_b32_e32 v26, 16, v100
	v_and_b32_e32 v27, 0xffff0000, v100
	v_lshlrev_b32_e32 v28, 16, v101
	v_and_b32_e32 v29, 0xffff0000, v101
	v_lshlrev_b32_e32 v30, 16, v102
	v_and_b32_e32 v31, 0xffff0000, v102
	v_lshlrev_b32_e32 v32, 16, v103
	v_and_b32_e32 v33, 0xffff0000, v103
	global_store_dwordx4 v[36:37], v[22:25], off
	v_lshl_add_u64 v[36:37], v[36:37], 0, s[12:13]
	v_pk_fma_f32 v[12:13], v[12:13], v[166:167], v[26:27]
	v_pk_fma_f32 v[14:15], v[14:15], v[168:169], v[28:29]
	v_pk_fma_f32 v[16:17], v[16:17], v[234:235], v[30:31]
	v_pk_fma_f32 v[18:19], v[18:19], v[236:237], v[32:33]
	global_load_dwordx4 v[92:95], v[34:35], off
	global_load_dwordx4 v[158:161], v[38:39], off
	global_load_dwordx4 v[226:229], v[38:39], off offset:16
	v_lshl_add_u64 v[34:35], v[34:35], 0, s[12:13]
	v_lshl_add_u64 v[38:39], v[38:39], 0, s[14:15]
	s_waitcnt vmcnt(52)
	v_cvt_pk_bf16_f32 v0, v12, v13
	v_cvt_pk_bf16_f32 v1, v14, v15
	v_cvt_pk_bf16_f32 v2, v16, v17
	v_cvt_pk_bf16_f32 v3, v18, v19
	v_lshlrev_b32_e32 v26, 16, v40
	v_and_b32_e32 v27, 0xffff0000, v40
	v_lshlrev_b32_e32 v28, 16, v41
	v_and_b32_e32 v29, 0xffff0000, v41
	v_lshlrev_b32_e32 v30, 16, v42
	v_and_b32_e32 v31, 0xffff0000, v42
	v_lshlrev_b32_e32 v32, 16, v43
	v_and_b32_e32 v33, 0xffff0000, v43
	global_store_dwordx4 v[36:37], v[0:3], off
	v_lshl_add_u64 v[36:37], v[36:37], 0, s[12:13]
	v_pk_fma_f32 v[12:13], v[12:13], v[104:105], v[26:27]
	v_pk_fma_f32 v[14:15], v[14:15], v[106:107], v[28:29]
	v_pk_fma_f32 v[16:17], v[16:17], v[170:171], v[30:31]
	v_pk_fma_f32 v[18:19], v[18:19], v[172:173], v[32:33]
	global_load_dwordx4 v[96:99], v[34:35], off
	global_load_dwordx4 v[162:165], v[38:39], off
	global_load_dwordx4 v[230:233], v[38:39], off offset:16
	v_lshl_add_u64 v[34:35], v[34:35], 0, s[12:13]
	v_lshl_add_u64 v[38:39], v[38:39], 0, s[14:15]
	s_waitcnt vmcnt(52)
	v_cvt_pk_bf16_f32 v22, v12, v13
	v_cvt_pk_bf16_f32 v23, v14, v15
	v_cvt_pk_bf16_f32 v24, v16, v17
	v_cvt_pk_bf16_f32 v25, v18, v19
	v_lshlrev_b32_e32 v26, 16, v44
	v_and_b32_e32 v27, 0xffff0000, v44
	v_lshlrev_b32_e32 v28, 16, v45
	v_and_b32_e32 v29, 0xffff0000, v45
	v_lshlrev_b32_e32 v30, 16, v46
	v_and_b32_e32 v31, 0xffff0000, v46
	v_lshlrev_b32_e32 v32, 16, v47
	v_and_b32_e32 v33, 0xffff0000, v47
	global_store_dwordx4 v[36:37], v[22:25], off
	v_lshl_add_u64 v[36:37], v[36:37], 0, s[12:13]
	v_pk_fma_f32 v[12:13], v[12:13], v[108:109], v[26:27]
	v_pk_fma_f32 v[14:15], v[14:15], v[110:111], v[28:29]
	v_pk_fma_f32 v[16:17], v[16:17], v[174:175], v[30:31]
	v_pk_fma_f32 v[18:19], v[18:19], v[176:177], v[32:33]
	global_load_dwordx4 v[100:103], v[34:35], off
	global_load_dwordx4 v[166:169], v[38:39], off
	global_load_dwordx4 v[234:237], v[38:39], off offset:16
	v_lshl_add_u64 v[34:35], v[34:35], 0, s[12:13]
	v_lshl_add_u64 v[38:39], v[38:39], 0, s[14:15]
	s_waitcnt vmcnt(52)
	v_cvt_pk_bf16_f32 v0, v12, v13
	v_cvt_pk_bf16_f32 v1, v14, v15
	v_cvt_pk_bf16_f32 v2, v16, v17
	v_cvt_pk_bf16_f32 v3, v18, v19
	v_lshlrev_b32_e32 v26, 16, v48
	v_and_b32_e32 v27, 0xffff0000, v48
	v_lshlrev_b32_e32 v28, 16, v49
	v_and_b32_e32 v29, 0xffff0000, v49
	v_lshlrev_b32_e32 v30, 16, v50
	v_and_b32_e32 v31, 0xffff0000, v50
	v_lshlrev_b32_e32 v32, 16, v51
	v_and_b32_e32 v33, 0xffff0000, v51
	global_store_dwordx4 v[36:37], v[0:3], off
	v_lshl_add_u64 v[36:37], v[36:37], 0, s[12:13]
	v_pk_fma_f32 v[12:13], v[12:13], v[112:113], v[26:27]
	v_pk_fma_f32 v[14:15], v[14:15], v[114:115], v[28:29]
	v_pk_fma_f32 v[16:17], v[16:17], v[178:179], v[30:31]
	v_pk_fma_f32 v[18:19], v[18:19], v[180:181], v[32:33]
	global_load_dwordx4 v[40:43], v[34:35], off
	global_load_dwordx4 v[104:107], v[38:39], off
	global_load_dwordx4 v[170:173], v[38:39], off offset:16
	v_lshl_add_u64 v[34:35], v[34:35], 0, s[12:13]
	v_lshl_add_u64 v[38:39], v[38:39], 0, s[14:15]
	s_waitcnt vmcnt(52)
	v_cvt_pk_bf16_f32 v22, v12, v13
	v_cvt_pk_bf16_f32 v23, v14, v15
	v_cvt_pk_bf16_f32 v24, v16, v17
	v_cvt_pk_bf16_f32 v25, v18, v19
	v_lshlrev_b32_e32 v26, 16, v52
	v_and_b32_e32 v27, 0xffff0000, v52
	v_lshlrev_b32_e32 v28, 16, v53
	v_and_b32_e32 v29, 0xffff0000, v53
	v_lshlrev_b32_e32 v30, 16, v54
	v_and_b32_e32 v31, 0xffff0000, v54
	v_lshlrev_b32_e32 v32, 16, v55
	v_and_b32_e32 v33, 0xffff0000, v55
	global_store_dwordx4 v[36:37], v[22:25], off
	v_lshl_add_u64 v[36:37], v[36:37], 0, s[12:13]
	v_pk_fma_f32 v[12:13], v[12:13], v[116:117], v[26:27]
	v_pk_fma_f32 v[14:15], v[14:15], v[118:119], v[28:29]
	v_pk_fma_f32 v[16:17], v[16:17], v[186:187], v[30:31]
	v_pk_fma_f32 v[18:19], v[18:19], v[188:189], v[32:33]
	global_load_dwordx4 v[44:47], v[34:35], off
	global_load_dwordx4 v[108:111], v[38:39], off
	global_load_dwordx4 v[174:177], v[38:39], off offset:16
	v_lshl_add_u64 v[34:35], v[34:35], 0, s[12:13]
	v_lshl_add_u64 v[38:39], v[38:39], 0, s[14:15]
	s_waitcnt vmcnt(52)
	v_cvt_pk_bf16_f32 v0, v12, v13
	v_cvt_pk_bf16_f32 v1, v14, v15
	v_cvt_pk_bf16_f32 v2, v16, v17
	v_cvt_pk_bf16_f32 v3, v18, v19
	v_lshlrev_b32_e32 v26, 16, v56
	v_and_b32_e32 v27, 0xffff0000, v56
	v_lshlrev_b32_e32 v28, 16, v57
	v_and_b32_e32 v29, 0xffff0000, v57
	v_lshlrev_b32_e32 v30, 16, v58
	v_and_b32_e32 v31, 0xffff0000, v58
	v_lshlrev_b32_e32 v32, 16, v59
	v_and_b32_e32 v33, 0xffff0000, v59
	global_store_dwordx4 v[36:37], v[0:3], off
	v_lshl_add_u64 v[36:37], v[36:37], 0, s[12:13]
	v_pk_fma_f32 v[12:13], v[12:13], v[120:121], v[26:27]
	v_pk_fma_f32 v[14:15], v[14:15], v[122:123], v[28:29]
	v_pk_fma_f32 v[16:17], v[16:17], v[190:191], v[30:31]
	v_pk_fma_f32 v[18:19], v[18:19], v[192:193], v[32:33]
	global_load_dwordx4 v[48:51], v[34:35], off
	global_load_dwordx4 v[112:115], v[38:39], off
	global_load_dwordx4 v[178:181], v[38:39], off offset:16
	v_lshl_add_u64 v[34:35], v[34:35], 0, s[12:13]
	v_lshl_add_u64 v[38:39], v[38:39], 0, s[14:15]
	s_waitcnt vmcnt(52)
	v_cvt_pk_bf16_f32 v22, v12, v13
	v_cvt_pk_bf16_f32 v23, v14, v15
	v_cvt_pk_bf16_f32 v24, v16, v17
	v_cvt_pk_bf16_f32 v25, v18, v19
	v_lshlrev_b32_e32 v26, 16, v60
	v_and_b32_e32 v27, 0xffff0000, v60
	v_lshlrev_b32_e32 v28, 16, v61
	v_and_b32_e32 v29, 0xffff0000, v61
	v_lshlrev_b32_e32 v30, 16, v62
	v_and_b32_e32 v31, 0xffff0000, v62
	v_lshlrev_b32_e32 v32, 16, v63
	v_and_b32_e32 v33, 0xffff0000, v63
	global_store_dwordx4 v[36:37], v[22:25], off
	v_lshl_add_u64 v[36:37], v[36:37], 0, s[12:13]
	v_pk_fma_f32 v[12:13], v[12:13], v[124:125], v[26:27]
	v_pk_fma_f32 v[14:15], v[14:15], v[126:127], v[28:29]
	v_pk_fma_f32 v[16:17], v[16:17], v[194:195], v[30:31]
	v_pk_fma_f32 v[18:19], v[18:19], v[196:197], v[32:33]
	global_load_dwordx4 v[52:55], v[34:35], off
	global_load_dwordx4 v[116:119], v[38:39], off
	global_load_dwordx4 v[186:189], v[38:39], off offset:16
	v_lshl_add_u64 v[34:35], v[34:35], 0, s[12:13]
	v_lshl_add_u64 v[38:39], v[38:39], 0, s[14:15]
	s_waitcnt vmcnt(52)
	v_cvt_pk_bf16_f32 v0, v12, v13
	v_cvt_pk_bf16_f32 v1, v14, v15
	v_cvt_pk_bf16_f32 v2, v16, v17
	v_cvt_pk_bf16_f32 v3, v18, v19
	v_lshlrev_b32_e32 v26, 16, v64
	v_and_b32_e32 v27, 0xffff0000, v64
	v_lshlrev_b32_e32 v28, 16, v65
	v_and_b32_e32 v29, 0xffff0000, v65
	v_lshlrev_b32_e32 v30, 16, v66
	v_and_b32_e32 v31, 0xffff0000, v66
	v_lshlrev_b32_e32 v32, 16, v67
	v_and_b32_e32 v33, 0xffff0000, v67
	global_store_dwordx4 v[36:37], v[0:3], off
	v_lshl_add_u64 v[36:37], v[36:37], 0, s[12:13]
	v_pk_fma_f32 v[12:13], v[12:13], v[128:129], v[26:27]
	v_pk_fma_f32 v[14:15], v[14:15], v[130:131], v[28:29]
	v_pk_fma_f32 v[16:17], v[16:17], v[198:199], v[30:31]
	v_pk_fma_f32 v[18:19], v[18:19], v[200:201], v[32:33]
	global_load_dwordx4 v[56:59], v[34:35], off
	global_load_dwordx4 v[120:123], v[38:39], off
	global_load_dwordx4 v[190:193], v[38:39], off offset:16
	v_lshl_add_u64 v[34:35], v[34:35], 0, s[12:13]
	v_lshl_add_u64 v[38:39], v[38:39], 0, s[14:15]
	s_waitcnt vmcnt(52)
	v_cvt_pk_bf16_f32 v22, v12, v13
	v_cvt_pk_bf16_f32 v23, v14, v15
	v_cvt_pk_bf16_f32 v24, v16, v17
	v_cvt_pk_bf16_f32 v25, v18, v19
	v_lshlrev_b32_e32 v26, 16, v68
	v_and_b32_e32 v27, 0xffff0000, v68
	v_lshlrev_b32_e32 v28, 16, v69
	v_and_b32_e32 v29, 0xffff0000, v69
	v_lshlrev_b32_e32 v30, 16, v70
	v_and_b32_e32 v31, 0xffff0000, v70
	v_lshlrev_b32_e32 v32, 16, v71
	v_and_b32_e32 v33, 0xffff0000, v71
	global_store_dwordx4 v[36:37], v[22:25], off
	v_lshl_add_u64 v[36:37], v[36:37], 0, s[12:13]
	v_pk_fma_f32 v[12:13], v[12:13], v[132:133], v[26:27]
	v_pk_fma_f32 v[14:15], v[14:15], v[134:135], v[28:29]
	v_pk_fma_f32 v[16:17], v[16:17], v[202:203], v[30:31]
	v_pk_fma_f32 v[18:19], v[18:19], v[204:205], v[32:33]
	global_load_dwordx4 v[60:63], v[34:35], off
	global_load_dwordx4 v[124:127], v[38:39], off
	global_load_dwordx4 v[194:197], v[38:39], off offset:16
	v_lshl_add_u64 v[34:35], v[34:35], 0, s[12:13]
	v_lshl_add_u64 v[38:39], v[38:39], 0, s[14:15]
	s_waitcnt vmcnt(52)
	v_cvt_pk_bf16_f32 v0, v12, v13
	v_cvt_pk_bf16_f32 v1, v14, v15
	v_cvt_pk_bf16_f32 v2, v16, v17
	v_cvt_pk_bf16_f32 v3, v18, v19
	v_lshlrev_b32_e32 v26, 16, v72
	v_and_b32_e32 v27, 0xffff0000, v72
	v_lshlrev_b32_e32 v28, 16, v73
	v_and_b32_e32 v29, 0xffff0000, v73
	v_lshlrev_b32_e32 v30, 16, v74
	v_and_b32_e32 v31, 0xffff0000, v74
	v_lshlrev_b32_e32 v32, 16, v75
	v_and_b32_e32 v33, 0xffff0000, v75
	global_store_dwordx4 v[36:37], v[0:3], off
	v_lshl_add_u64 v[36:37], v[36:37], 0, s[12:13]
	v_pk_fma_f32 v[12:13], v[12:13], v[136:137], v[26:27]
	v_pk_fma_f32 v[14:15], v[14:15], v[138:139], v[28:29]
	v_pk_fma_f32 v[16:17], v[16:17], v[206:207], v[30:31]
	v_pk_fma_f32 v[18:19], v[18:19], v[208:209], v[32:33]
	global_load_dwordx4 v[64:67], v[34:35], off
	global_load_dwordx4 v[128:131], v[38:39], off
	global_load_dwordx4 v[198:201], v[38:39], off offset:16
	v_lshl_add_u64 v[34:35], v[34:35], 0, s[12:13]
	v_lshl_add_u64 v[38:39], v[38:39], 0, s[14:15]
	s_waitcnt vmcnt(52)
	v_cvt_pk_bf16_f32 v22, v12, v13
	v_cvt_pk_bf16_f32 v23, v14, v15
	v_cvt_pk_bf16_f32 v24, v16, v17
	v_cvt_pk_bf16_f32 v25, v18, v19
	v_lshlrev_b32_e32 v26, 16, v76
	v_and_b32_e32 v27, 0xffff0000, v76
	v_lshlrev_b32_e32 v28, 16, v77
	v_and_b32_e32 v29, 0xffff0000, v77
	v_lshlrev_b32_e32 v30, 16, v78
	v_and_b32_e32 v31, 0xffff0000, v78
	v_lshlrev_b32_e32 v32, 16, v79
	v_and_b32_e32 v33, 0xffff0000, v79
	global_store_dwordx4 v[36:37], v[22:25], off
	v_lshl_add_u64 v[36:37], v[36:37], 0, s[12:13]
	v_pk_fma_f32 v[12:13], v[12:13], v[140:141], v[26:27]
	v_pk_fma_f32 v[14:15], v[14:15], v[142:143], v[28:29]
	v_pk_fma_f32 v[16:17], v[16:17], v[210:211], v[30:31]
	v_pk_fma_f32 v[18:19], v[18:19], v[212:213], v[32:33]
	global_load_dwordx4 v[68:71], v[34:35], off
	global_load_dwordx4 v[132:135], v[38:39], off
	global_load_dwordx4 v[202:205], v[38:39], off offset:16
	v_lshl_add_u64 v[34:35], v[34:35], 0, s[12:13]
	v_lshl_add_u64 v[38:39], v[38:39], 0, s[14:15]
	s_waitcnt vmcnt(52)
	v_cvt_pk_bf16_f32 v0, v12, v13
	v_cvt_pk_bf16_f32 v1, v14, v15
	v_cvt_pk_bf16_f32 v2, v16, v17
	v_cvt_pk_bf16_f32 v3, v18, v19
	v_lshlrev_b32_e32 v26, 16, v80
	v_and_b32_e32 v27, 0xffff0000, v80
	v_lshlrev_b32_e32 v28, 16, v81
	v_and_b32_e32 v29, 0xffff0000, v81
	v_lshlrev_b32_e32 v30, 16, v82
	v_and_b32_e32 v31, 0xffff0000, v82
	v_lshlrev_b32_e32 v32, 16, v83
	v_and_b32_e32 v33, 0xffff0000, v83
	global_store_dwordx4 v[36:37], v[0:3], off
	v_lshl_add_u64 v[36:37], v[36:37], 0, s[12:13]
	v_pk_fma_f32 v[12:13], v[12:13], v[146:147], v[26:27]
	v_pk_fma_f32 v[14:15], v[14:15], v[148:149], v[28:29]
	v_pk_fma_f32 v[16:17], v[16:17], v[214:215], v[30:31]
	v_pk_fma_f32 v[18:19], v[18:19], v[216:217], v[32:33]
	global_load_dwordx4 v[72:75], v[34:35], off
	global_load_dwordx4 v[136:139], v[38:39], off
	global_load_dwordx4 v[206:209], v[38:39], off offset:16
	v_lshl_add_u64 v[34:35], v[34:35], 0, s[12:13]
	v_lshl_add_u64 v[38:39], v[38:39], 0, s[14:15]
	s_waitcnt vmcnt(52)
	v_cvt_pk_bf16_f32 v22, v12, v13
	v_cvt_pk_bf16_f32 v23, v14, v15
	v_cvt_pk_bf16_f32 v24, v16, v17
	v_cvt_pk_bf16_f32 v25, v18, v19
	v_lshlrev_b32_e32 v26, 16, v84
	v_and_b32_e32 v27, 0xffff0000, v84
	v_lshlrev_b32_e32 v28, 16, v85
	v_and_b32_e32 v29, 0xffff0000, v85
	v_lshlrev_b32_e32 v30, 16, v86
	v_and_b32_e32 v31, 0xffff0000, v86
	v_lshlrev_b32_e32 v32, 16, v87
	v_and_b32_e32 v33, 0xffff0000, v87
	global_store_dwordx4 v[36:37], v[22:25], off
	v_lshl_add_u64 v[36:37], v[36:37], 0, s[12:13]
	v_pk_fma_f32 v[12:13], v[12:13], v[150:151], v[26:27]
	v_pk_fma_f32 v[14:15], v[14:15], v[152:153], v[28:29]
	v_pk_fma_f32 v[16:17], v[16:17], v[218:219], v[30:31]
	v_pk_fma_f32 v[18:19], v[18:19], v[220:221], v[32:33]
	global_load_dwordx4 v[76:79], v[34:35], off
	global_load_dwordx4 v[140:143], v[38:39], off
	global_load_dwordx4 v[210:213], v[38:39], off offset:16
	v_lshl_add_u64 v[34:35], v[34:35], 0, s[12:13]
	v_lshl_add_u64 v[38:39], v[38:39], 0, s[14:15]
	s_waitcnt vmcnt(52)
	v_cvt_pk_bf16_f32 v0, v12, v13
	v_cvt_pk_bf16_f32 v1, v14, v15
	v_cvt_pk_bf16_f32 v2, v16, v17
	v_cvt_pk_bf16_f32 v3, v18, v19
	v_lshlrev_b32_e32 v26, 16, v88
	v_and_b32_e32 v27, 0xffff0000, v88
	v_lshlrev_b32_e32 v28, 16, v89
	v_and_b32_e32 v29, 0xffff0000, v89
	v_lshlrev_b32_e32 v30, 16, v90
	v_and_b32_e32 v31, 0xffff0000, v90
	v_lshlrev_b32_e32 v32, 16, v91
	v_and_b32_e32 v33, 0xffff0000, v91
	global_store_dwordx4 v[36:37], v[0:3], off
	v_lshl_add_u64 v[36:37], v[36:37], 0, s[12:13]
	v_pk_fma_f32 v[12:13], v[12:13], v[154:155], v[26:27]
	v_pk_fma_f32 v[14:15], v[14:15], v[156:157], v[28:29]
	v_pk_fma_f32 v[16:17], v[16:17], v[222:223], v[30:31]
	v_pk_fma_f32 v[18:19], v[18:19], v[224:225], v[32:33]
	global_load_dwordx4 v[80:83], v[34:35], off
	global_load_dwordx4 v[146:149], v[38:39], off
	global_load_dwordx4 v[214:217], v[38:39], off offset:16
	v_lshl_add_u64 v[34:35], v[34:35], 0, s[12:13]
	v_lshl_add_u64 v[38:39], v[38:39], 0, s[14:15]
	s_waitcnt vmcnt(52)
	v_cvt_pk_bf16_f32 v22, v12, v13
	v_cvt_pk_bf16_f32 v23, v14, v15
	v_cvt_pk_bf16_f32 v24, v16, v17
	v_cvt_pk_bf16_f32 v25, v18, v19
	v_lshlrev_b32_e32 v26, 16, v92
	v_and_b32_e32 v27, 0xffff0000, v92
	v_lshlrev_b32_e32 v28, 16, v93
	v_and_b32_e32 v29, 0xffff0000, v93
	v_lshlrev_b32_e32 v30, 16, v94
	v_and_b32_e32 v31, 0xffff0000, v94
	v_lshlrev_b32_e32 v32, 16, v95
	v_and_b32_e32 v33, 0xffff0000, v95
	global_store_dwordx4 v[36:37], v[22:25], off
	v_lshl_add_u64 v[36:37], v[36:37], 0, s[12:13]
	v_pk_fma_f32 v[12:13], v[12:13], v[158:159], v[26:27]
	v_pk_fma_f32 v[14:15], v[14:15], v[160:161], v[28:29]
	v_pk_fma_f32 v[16:17], v[16:17], v[226:227], v[30:31]
	v_pk_fma_f32 v[18:19], v[18:19], v[228:229], v[32:33]
	global_load_dwordx4 v[84:87], v[34:35], off
	global_load_dwordx4 v[150:153], v[38:39], off
	global_load_dwordx4 v[218:221], v[38:39], off offset:16
	v_lshl_add_u64 v[34:35], v[34:35], 0, s[12:13]
	v_lshl_add_u64 v[38:39], v[38:39], 0, s[14:15]
	s_waitcnt vmcnt(52)
	v_cvt_pk_bf16_f32 v0, v12, v13
	v_cvt_pk_bf16_f32 v1, v14, v15
	v_cvt_pk_bf16_f32 v2, v16, v17
	v_cvt_pk_bf16_f32 v3, v18, v19
	v_lshlrev_b32_e32 v26, 16, v96
	v_and_b32_e32 v27, 0xffff0000, v96
	v_lshlrev_b32_e32 v28, 16, v97
	v_and_b32_e32 v29, 0xffff0000, v97
	v_lshlrev_b32_e32 v30, 16, v98
	v_and_b32_e32 v31, 0xffff0000, v98
	v_lshlrev_b32_e32 v32, 16, v99
	v_and_b32_e32 v33, 0xffff0000, v99
	global_store_dwordx4 v[36:37], v[0:3], off
	v_lshl_add_u64 v[36:37], v[36:37], 0, s[12:13]
	v_pk_fma_f32 v[12:13], v[12:13], v[162:163], v[26:27]
	v_pk_fma_f32 v[14:15], v[14:15], v[164:165], v[28:29]
	v_pk_fma_f32 v[16:17], v[16:17], v[230:231], v[30:31]
	v_pk_fma_f32 v[18:19], v[18:19], v[232:233], v[32:33]
	global_load_dwordx4 v[88:91], v[34:35], off
	global_load_dwordx4 v[154:157], v[38:39], off
	global_load_dwordx4 v[222:225], v[38:39], off offset:16
	v_lshl_add_u64 v[34:35], v[34:35], 0, s[12:13]
	v_lshl_add_u64 v[38:39], v[38:39], 0, s[14:15]
	s_waitcnt vmcnt(52)
	v_cvt_pk_bf16_f32 v22, v12, v13
	v_cvt_pk_bf16_f32 v23, v14, v15
	v_cvt_pk_bf16_f32 v24, v16, v17
	v_cvt_pk_bf16_f32 v25, v18, v19
	v_lshlrev_b32_e32 v26, 16, v100
	v_and_b32_e32 v27, 0xffff0000, v100
	v_lshlrev_b32_e32 v28, 16, v101
	v_and_b32_e32 v29, 0xffff0000, v101
	v_lshlrev_b32_e32 v30, 16, v102
	v_and_b32_e32 v31, 0xffff0000, v102
	v_lshlrev_b32_e32 v32, 16, v103
	v_and_b32_e32 v33, 0xffff0000, v103
	global_store_dwordx4 v[36:37], v[22:25], off
	v_lshl_add_u64 v[36:37], v[36:37], 0, s[12:13]
	v_pk_fma_f32 v[12:13], v[12:13], v[166:167], v[26:27]
	v_pk_fma_f32 v[14:15], v[14:15], v[168:169], v[28:29]
	v_pk_fma_f32 v[16:17], v[16:17], v[234:235], v[30:31]
	v_pk_fma_f32 v[18:19], v[18:19], v[236:237], v[32:33]
	global_load_dwordx4 v[92:95], v[34:35], off
	global_load_dwordx4 v[158:161], v[38:39], off
	global_load_dwordx4 v[226:229], v[38:39], off offset:16
	v_lshl_add_u64 v[34:35], v[34:35], 0, s[12:13]
	v_lshl_add_u64 v[38:39], v[38:39], 0, s[14:15]
	s_waitcnt vmcnt(52)
	v_cvt_pk_bf16_f32 v0, v12, v13
	v_cvt_pk_bf16_f32 v1, v14, v15
	v_cvt_pk_bf16_f32 v2, v16, v17
	v_cvt_pk_bf16_f32 v3, v18, v19
	v_lshlrev_b32_e32 v26, 16, v40
	v_and_b32_e32 v27, 0xffff0000, v40
	v_lshlrev_b32_e32 v28, 16, v41
	v_and_b32_e32 v29, 0xffff0000, v41
	v_lshlrev_b32_e32 v30, 16, v42
	v_and_b32_e32 v31, 0xffff0000, v42
	v_lshlrev_b32_e32 v32, 16, v43
	v_and_b32_e32 v33, 0xffff0000, v43
	global_store_dwordx4 v[36:37], v[0:3], off
	v_lshl_add_u64 v[36:37], v[36:37], 0, s[12:13]
	v_pk_fma_f32 v[12:13], v[12:13], v[104:105], v[26:27]
	v_pk_fma_f32 v[14:15], v[14:15], v[106:107], v[28:29]
	v_pk_fma_f32 v[16:17], v[16:17], v[170:171], v[30:31]
	v_pk_fma_f32 v[18:19], v[18:19], v[172:173], v[32:33]
	global_load_dwordx4 v[96:99], v[34:35], off
	global_load_dwordx4 v[162:165], v[38:39], off
	global_load_dwordx4 v[230:233], v[38:39], off offset:16
	v_lshl_add_u64 v[34:35], v[34:35], 0, s[12:13]
	v_lshl_add_u64 v[38:39], v[38:39], 0, s[14:15]
	s_waitcnt vmcnt(52)
	v_cvt_pk_bf16_f32 v22, v12, v13
	v_cvt_pk_bf16_f32 v23, v14, v15
	v_cvt_pk_bf16_f32 v24, v16, v17
	v_cvt_pk_bf16_f32 v25, v18, v19
	v_lshlrev_b32_e32 v26, 16, v44
	v_and_b32_e32 v27, 0xffff0000, v44
	v_lshlrev_b32_e32 v28, 16, v45
	v_and_b32_e32 v29, 0xffff0000, v45
	v_lshlrev_b32_e32 v30, 16, v46
	v_and_b32_e32 v31, 0xffff0000, v46
	v_lshlrev_b32_e32 v32, 16, v47
	v_and_b32_e32 v33, 0xffff0000, v47
	global_store_dwordx4 v[36:37], v[22:25], off
	v_lshl_add_u64 v[36:37], v[36:37], 0, s[12:13]
	v_pk_fma_f32 v[12:13], v[12:13], v[108:109], v[26:27]
	v_pk_fma_f32 v[14:15], v[14:15], v[110:111], v[28:29]
	v_pk_fma_f32 v[16:17], v[16:17], v[174:175], v[30:31]
	v_pk_fma_f32 v[18:19], v[18:19], v[176:177], v[32:33]
	global_load_dwordx4 v[100:103], v[34:35], off
	global_load_dwordx4 v[166:169], v[38:39], off
	global_load_dwordx4 v[234:237], v[38:39], off offset:16
	v_lshl_add_u64 v[34:35], v[34:35], 0, s[12:13]
	v_lshl_add_u64 v[38:39], v[38:39], 0, s[14:15]
	s_waitcnt vmcnt(52)
	v_cvt_pk_bf16_f32 v0, v12, v13
	v_cvt_pk_bf16_f32 v1, v14, v15
	v_cvt_pk_bf16_f32 v2, v16, v17
	v_cvt_pk_bf16_f32 v3, v18, v19
	v_lshlrev_b32_e32 v26, 16, v48
	v_and_b32_e32 v27, 0xffff0000, v48
	v_lshlrev_b32_e32 v28, 16, v49
	v_and_b32_e32 v29, 0xffff0000, v49
	v_lshlrev_b32_e32 v30, 16, v50
	v_and_b32_e32 v31, 0xffff0000, v50
	v_lshlrev_b32_e32 v32, 16, v51
	v_and_b32_e32 v33, 0xffff0000, v51
	global_store_dwordx4 v[36:37], v[0:3], off
	v_lshl_add_u64 v[36:37], v[36:37], 0, s[12:13]
	v_pk_fma_f32 v[12:13], v[12:13], v[112:113], v[26:27]
	v_pk_fma_f32 v[14:15], v[14:15], v[114:115], v[28:29]
	v_pk_fma_f32 v[16:17], v[16:17], v[178:179], v[30:31]
	v_pk_fma_f32 v[18:19], v[18:19], v[180:181], v[32:33]
	s_waitcnt vmcnt(49)
	v_cvt_pk_bf16_f32 v22, v12, v13
	v_cvt_pk_bf16_f32 v23, v14, v15
	v_cvt_pk_bf16_f32 v24, v16, v17
	v_cvt_pk_bf16_f32 v25, v18, v19
	v_lshlrev_b32_e32 v26, 16, v52
	v_and_b32_e32 v27, 0xffff0000, v52
	v_lshlrev_b32_e32 v28, 16, v53
	v_and_b32_e32 v29, 0xffff0000, v53
	v_lshlrev_b32_e32 v30, 16, v54
	v_and_b32_e32 v31, 0xffff0000, v54
	v_lshlrev_b32_e32 v32, 16, v55
	v_and_b32_e32 v33, 0xffff0000, v55
	global_store_dwordx4 v[36:37], v[22:25], off
	v_lshl_add_u64 v[36:37], v[36:37], 0, s[12:13]
	v_pk_fma_f32 v[12:13], v[12:13], v[116:117], v[26:27]
	v_pk_fma_f32 v[14:15], v[14:15], v[118:119], v[28:29]
	v_pk_fma_f32 v[16:17], v[16:17], v[186:187], v[30:31]
	v_pk_fma_f32 v[18:19], v[18:19], v[188:189], v[32:33]
	s_waitcnt vmcnt(46)
	v_cvt_pk_bf16_f32 v0, v12, v13
	v_cvt_pk_bf16_f32 v1, v14, v15
	v_cvt_pk_bf16_f32 v2, v16, v17
	v_cvt_pk_bf16_f32 v3, v18, v19
	v_lshlrev_b32_e32 v26, 16, v56
	v_and_b32_e32 v27, 0xffff0000, v56
	v_lshlrev_b32_e32 v28, 16, v57
	v_and_b32_e32 v29, 0xffff0000, v57
	v_lshlrev_b32_e32 v30, 16, v58
	v_and_b32_e32 v31, 0xffff0000, v58
	v_lshlrev_b32_e32 v32, 16, v59
	v_and_b32_e32 v33, 0xffff0000, v59
	global_store_dwordx4 v[36:37], v[0:3], off
	v_lshl_add_u64 v[36:37], v[36:37], 0, s[12:13]
	v_pk_fma_f32 v[12:13], v[12:13], v[120:121], v[26:27]
	v_pk_fma_f32 v[14:15], v[14:15], v[122:123], v[28:29]
	v_pk_fma_f32 v[16:17], v[16:17], v[190:191], v[30:31]
	v_pk_fma_f32 v[18:19], v[18:19], v[192:193], v[32:33]
	s_waitcnt vmcnt(43)
	v_cvt_pk_bf16_f32 v22, v12, v13
	v_cvt_pk_bf16_f32 v23, v14, v15
	v_cvt_pk_bf16_f32 v24, v16, v17
	v_cvt_pk_bf16_f32 v25, v18, v19
	v_lshlrev_b32_e32 v26, 16, v60
	v_and_b32_e32 v27, 0xffff0000, v60
	v_lshlrev_b32_e32 v28, 16, v61
	v_and_b32_e32 v29, 0xffff0000, v61
	v_lshlrev_b32_e32 v30, 16, v62
	v_and_b32_e32 v31, 0xffff0000, v62
	v_lshlrev_b32_e32 v32, 16, v63
	v_and_b32_e32 v33, 0xffff0000, v63
	global_store_dwordx4 v[36:37], v[22:25], off
	v_lshl_add_u64 v[36:37], v[36:37], 0, s[12:13]
	v_pk_fma_f32 v[12:13], v[12:13], v[124:125], v[26:27]
	v_pk_fma_f32 v[14:15], v[14:15], v[126:127], v[28:29]
	v_pk_fma_f32 v[16:17], v[16:17], v[194:195], v[30:31]
	v_pk_fma_f32 v[18:19], v[18:19], v[196:197], v[32:33]
	s_waitcnt vmcnt(40)
	v_cvt_pk_bf16_f32 v0, v12, v13
	v_cvt_pk_bf16_f32 v1, v14, v15
	v_cvt_pk_bf16_f32 v2, v16, v17
	v_cvt_pk_bf16_f32 v3, v18, v19
	v_lshlrev_b32_e32 v26, 16, v64
	v_and_b32_e32 v27, 0xffff0000, v64
	v_lshlrev_b32_e32 v28, 16, v65
	v_and_b32_e32 v29, 0xffff0000, v65
	v_lshlrev_b32_e32 v30, 16, v66
	v_and_b32_e32 v31, 0xffff0000, v66
	v_lshlrev_b32_e32 v32, 16, v67
	v_and_b32_e32 v33, 0xffff0000, v67
	global_store_dwordx4 v[36:37], v[0:3], off
	v_lshl_add_u64 v[36:37], v[36:37], 0, s[12:13]
	v_pk_fma_f32 v[12:13], v[12:13], v[128:129], v[26:27]
	v_pk_fma_f32 v[14:15], v[14:15], v[130:131], v[28:29]
	v_pk_fma_f32 v[16:17], v[16:17], v[198:199], v[30:31]
	v_pk_fma_f32 v[18:19], v[18:19], v[200:201], v[32:33]
	s_waitcnt vmcnt(37)
	v_cvt_pk_bf16_f32 v22, v12, v13
	v_cvt_pk_bf16_f32 v23, v14, v15
	v_cvt_pk_bf16_f32 v24, v16, v17
	v_cvt_pk_bf16_f32 v25, v18, v19
	v_lshlrev_b32_e32 v26, 16, v68
	v_and_b32_e32 v27, 0xffff0000, v68
	v_lshlrev_b32_e32 v28, 16, v69
	v_and_b32_e32 v29, 0xffff0000, v69
	v_lshlrev_b32_e32 v30, 16, v70
	v_and_b32_e32 v31, 0xffff0000, v70
	v_lshlrev_b32_e32 v32, 16, v71
	v_and_b32_e32 v33, 0xffff0000, v71
	global_store_dwordx4 v[36:37], v[22:25], off
	v_lshl_add_u64 v[36:37], v[36:37], 0, s[12:13]
	v_pk_fma_f32 v[12:13], v[12:13], v[132:133], v[26:27]
	v_pk_fma_f32 v[14:15], v[14:15], v[134:135], v[28:29]
	v_pk_fma_f32 v[16:17], v[16:17], v[202:203], v[30:31]
	v_pk_fma_f32 v[18:19], v[18:19], v[204:205], v[32:33]
	s_waitcnt vmcnt(34)
	v_cvt_pk_bf16_f32 v0, v12, v13
	v_cvt_pk_bf16_f32 v1, v14, v15
	v_cvt_pk_bf16_f32 v2, v16, v17
	v_cvt_pk_bf16_f32 v3, v18, v19
	v_lshlrev_b32_e32 v26, 16, v72
	v_and_b32_e32 v27, 0xffff0000, v72
	v_lshlrev_b32_e32 v28, 16, v73
	v_and_b32_e32 v29, 0xffff0000, v73
	v_lshlrev_b32_e32 v30, 16, v74
	v_and_b32_e32 v31, 0xffff0000, v74
	v_lshlrev_b32_e32 v32, 16, v75
	v_and_b32_e32 v33, 0xffff0000, v75
	global_store_dwordx4 v[36:37], v[0:3], off
	v_lshl_add_u64 v[36:37], v[36:37], 0, s[12:13]
	v_pk_fma_f32 v[12:13], v[12:13], v[136:137], v[26:27]
	v_pk_fma_f32 v[14:15], v[14:15], v[138:139], v[28:29]
	v_pk_fma_f32 v[16:17], v[16:17], v[206:207], v[30:31]
	v_pk_fma_f32 v[18:19], v[18:19], v[208:209], v[32:33]
	s_waitcnt vmcnt(31)
	v_cvt_pk_bf16_f32 v22, v12, v13
	v_cvt_pk_bf16_f32 v23, v14, v15
	v_cvt_pk_bf16_f32 v24, v16, v17
	v_cvt_pk_bf16_f32 v25, v18, v19
	v_lshlrev_b32_e32 v26, 16, v76
	v_and_b32_e32 v27, 0xffff0000, v76
	v_lshlrev_b32_e32 v28, 16, v77
	v_and_b32_e32 v29, 0xffff0000, v77
	v_lshlrev_b32_e32 v30, 16, v78
	v_and_b32_e32 v31, 0xffff0000, v78
	v_lshlrev_b32_e32 v32, 16, v79
	v_and_b32_e32 v33, 0xffff0000, v79
	global_store_dwordx4 v[36:37], v[22:25], off
	v_lshl_add_u64 v[36:37], v[36:37], 0, s[12:13]
	v_pk_fma_f32 v[12:13], v[12:13], v[140:141], v[26:27]
	v_pk_fma_f32 v[14:15], v[14:15], v[142:143], v[28:29]
	v_pk_fma_f32 v[16:17], v[16:17], v[210:211], v[30:31]
	v_pk_fma_f32 v[18:19], v[18:19], v[212:213], v[32:33]
	s_waitcnt vmcnt(28)
	v_cvt_pk_bf16_f32 v0, v12, v13
	v_cvt_pk_bf16_f32 v1, v14, v15
	v_cvt_pk_bf16_f32 v2, v16, v17
	v_cvt_pk_bf16_f32 v3, v18, v19
	v_lshlrev_b32_e32 v26, 16, v80
	v_and_b32_e32 v27, 0xffff0000, v80
	v_lshlrev_b32_e32 v28, 16, v81
	v_and_b32_e32 v29, 0xffff0000, v81
	v_lshlrev_b32_e32 v30, 16, v82
	v_and_b32_e32 v31, 0xffff0000, v82
	v_lshlrev_b32_e32 v32, 16, v83
	v_and_b32_e32 v33, 0xffff0000, v83
	global_store_dwordx4 v[36:37], v[0:3], off
	v_lshl_add_u64 v[36:37], v[36:37], 0, s[12:13]
	v_pk_fma_f32 v[12:13], v[12:13], v[146:147], v[26:27]
	v_pk_fma_f32 v[14:15], v[14:15], v[148:149], v[28:29]
	v_pk_fma_f32 v[16:17], v[16:17], v[214:215], v[30:31]
	v_pk_fma_f32 v[18:19], v[18:19], v[216:217], v[32:33]
	s_waitcnt vmcnt(25)
	v_cvt_pk_bf16_f32 v22, v12, v13
	v_cvt_pk_bf16_f32 v23, v14, v15
	v_cvt_pk_bf16_f32 v24, v16, v17
	v_cvt_pk_bf16_f32 v25, v18, v19
	v_lshlrev_b32_e32 v26, 16, v84
	v_and_b32_e32 v27, 0xffff0000, v84
	v_lshlrev_b32_e32 v28, 16, v85
	v_and_b32_e32 v29, 0xffff0000, v85
	v_lshlrev_b32_e32 v30, 16, v86
	v_and_b32_e32 v31, 0xffff0000, v86
	v_lshlrev_b32_e32 v32, 16, v87
	v_and_b32_e32 v33, 0xffff0000, v87
	global_store_dwordx4 v[36:37], v[22:25], off
	v_lshl_add_u64 v[36:37], v[36:37], 0, s[12:13]
	v_pk_fma_f32 v[12:13], v[12:13], v[150:151], v[26:27]
	v_pk_fma_f32 v[14:15], v[14:15], v[152:153], v[28:29]
	v_pk_fma_f32 v[16:17], v[16:17], v[218:219], v[30:31]
	v_pk_fma_f32 v[18:19], v[18:19], v[220:221], v[32:33]
	s_waitcnt vmcnt(22)
	v_cvt_pk_bf16_f32 v0, v12, v13
	v_cvt_pk_bf16_f32 v1, v14, v15
	v_cvt_pk_bf16_f32 v2, v16, v17
	v_cvt_pk_bf16_f32 v3, v18, v19
	v_lshlrev_b32_e32 v26, 16, v88
	v_and_b32_e32 v27, 0xffff0000, v88
	v_lshlrev_b32_e32 v28, 16, v89
	v_and_b32_e32 v29, 0xffff0000, v89
	v_lshlrev_b32_e32 v30, 16, v90
	v_and_b32_e32 v31, 0xffff0000, v90
	v_lshlrev_b32_e32 v32, 16, v91
	v_and_b32_e32 v33, 0xffff0000, v91
	global_store_dwordx4 v[36:37], v[0:3], off
	v_lshl_add_u64 v[36:37], v[36:37], 0, s[12:13]
	v_pk_fma_f32 v[12:13], v[12:13], v[154:155], v[26:27]
	v_pk_fma_f32 v[14:15], v[14:15], v[156:157], v[28:29]
	v_pk_fma_f32 v[16:17], v[16:17], v[222:223], v[30:31]
	v_pk_fma_f32 v[18:19], v[18:19], v[224:225], v[32:33]
	s_waitcnt vmcnt(19)
	v_cvt_pk_bf16_f32 v22, v12, v13
	v_cvt_pk_bf16_f32 v23, v14, v15
	v_cvt_pk_bf16_f32 v24, v16, v17
	v_cvt_pk_bf16_f32 v25, v18, v19
	v_lshlrev_b32_e32 v26, 16, v92
	v_and_b32_e32 v27, 0xffff0000, v92
	v_lshlrev_b32_e32 v28, 16, v93
	v_and_b32_e32 v29, 0xffff0000, v93
	v_lshlrev_b32_e32 v30, 16, v94
	v_and_b32_e32 v31, 0xffff0000, v94
	v_lshlrev_b32_e32 v32, 16, v95
	v_and_b32_e32 v33, 0xffff0000, v95
	global_store_dwordx4 v[36:37], v[22:25], off
	v_lshl_add_u64 v[36:37], v[36:37], 0, s[12:13]
	v_pk_fma_f32 v[12:13], v[12:13], v[158:159], v[26:27]
	v_pk_fma_f32 v[14:15], v[14:15], v[160:161], v[28:29]
	v_pk_fma_f32 v[16:17], v[16:17], v[226:227], v[30:31]
	v_pk_fma_f32 v[18:19], v[18:19], v[228:229], v[32:33]
	s_waitcnt vmcnt(16)
	v_cvt_pk_bf16_f32 v0, v12, v13
	v_cvt_pk_bf16_f32 v1, v14, v15
	v_cvt_pk_bf16_f32 v2, v16, v17
	v_cvt_pk_bf16_f32 v3, v18, v19
	v_lshlrev_b32_e32 v26, 16, v96
	v_and_b32_e32 v27, 0xffff0000, v96
	v_lshlrev_b32_e32 v28, 16, v97
	v_and_b32_e32 v29, 0xffff0000, v97
	v_lshlrev_b32_e32 v30, 16, v98
	v_and_b32_e32 v31, 0xffff0000, v98
	v_lshlrev_b32_e32 v32, 16, v99
	v_and_b32_e32 v33, 0xffff0000, v99
	global_store_dwordx4 v[36:37], v[0:3], off
	v_lshl_add_u64 v[36:37], v[36:37], 0, s[12:13]
	v_pk_fma_f32 v[12:13], v[12:13], v[162:163], v[26:27]
	v_pk_fma_f32 v[14:15], v[14:15], v[164:165], v[28:29]
	v_pk_fma_f32 v[16:17], v[16:17], v[230:231], v[30:31]
	v_pk_fma_f32 v[18:19], v[18:19], v[232:233], v[32:33]
	s_waitcnt vmcnt(13)
	v_cvt_pk_bf16_f32 v22, v12, v13
	v_cvt_pk_bf16_f32 v23, v14, v15
	v_cvt_pk_bf16_f32 v24, v16, v17
	v_cvt_pk_bf16_f32 v25, v18, v19
	v_lshlrev_b32_e32 v26, 16, v100
	v_and_b32_e32 v27, 0xffff0000, v100
	v_lshlrev_b32_e32 v28, 16, v101
	v_and_b32_e32 v29, 0xffff0000, v101
	v_lshlrev_b32_e32 v30, 16, v102
	v_and_b32_e32 v31, 0xffff0000, v102
	v_lshlrev_b32_e32 v32, 16, v103
	v_and_b32_e32 v33, 0xffff0000, v103
	global_store_dwordx4 v[36:37], v[22:25], off
	v_lshl_add_u64 v[36:37], v[36:37], 0, s[12:13]
	v_pk_fma_f32 v[12:13], v[12:13], v[166:167], v[26:27]
	v_pk_fma_f32 v[14:15], v[14:15], v[168:169], v[28:29]
	v_pk_fma_f32 v[16:17], v[16:17], v[234:235], v[30:31]
	v_pk_fma_f32 v[18:19], v[18:19], v[236:237], v[32:33]
	v_add_u32_e32 v20, s8, v20
	v_cmp_lt_i32_e32 vcc, s9, v20
	s_or_b64 s[6:7], vcc, s[6:7]
	s_andn2_b64 exec, exec, s[6:7]
	s_cbranch_execnz .LBB0_723
